# non-temporal (nt) hints on more read-once / write-once streams: residual-row loads in the two residual GEMM epilogues, final-norm output stores, weight-conversion source loads; on top of the norm-load
# baseline (speedup 1.0000x reference)
; DI void conv_job(const float* src0, const float* src1, int ld, int K, int N, bf16_t* dst, int kind, const float* kscale, char* smem, int& rot) {
;     ...
;     const int nt = it / kq, kt0 = (it - nt * kq) * 4, nkt = (ktn - kt0) < 4 ? (ktn - kt0) : 4;
;     const int n = nt * 64 + tx * 4;
;     const float* src = src0; int col = n;
;     if (kind == 1) {
;       if (n < 512) col = n;
;       else if (n < 768) col = 800 + (n - 512);
;       else if (n < 1024) col = 1952 + (n - 768);
;       else if (n < 1280) col = 512 + (n - 1024);
;       else if (n < 1664) col = 1568 + (n - 1280);
;       else if (n < 2176) col = 2208 + (n - 1664);
;       else if (n < 2688) col = 2720 + (n - 2176);
;       else if (n < 2720) col = 768 + (n - 2688);
;       else if (n < 2816) col = -1;
;       else col = 1056 + (n - 2816);
;     } else if (kind == 2) { col = 3232 + n;
;     } else if (kind == 4) { col = (n >> 6) * 128 + (n & 63);
;     } else if (kind == 5) { col = (n >> 6) * 128 + 64 + (n & 63);
;     } else if (kind == 6) { const int tl = n >> 8, c = n & 255; col = tl * 128 + (c & 127); src = (c >> 7) ? src1 : src0; }
;     float4 v[4][2];
; #pragma unroll
;     for (int q = 0; q < 4; ++q)
; #pragma unroll
;       for (int ps = 0; ps < 2; ++ps) {
;         v[q][ps] = make_float4(0.f, 0.f, 0.f, 0.f);
;         if (q < nkt && col >= 0) { const int k = (kt0 + q) * 64 + ty + 32 * ps; v[q][ps] = *(const float4*)(src + (size_t)k * ld + col); }
;       }
.LBB0_157:
	s_lshr_b32 s0, s4, 31
	s_add_i32 s0, s4, s0
	s_ashr_i32 s1, s0, 1
	s_and_b32 s0, s0, -2
	s_sub_i32 s13, s4, s0
	s_lshl_b32 s5, s1, 6
	s_cmp_gt_i32 s4, -2
	v_mov_b32_e32 v36, v192
	s_cselect_b64 s[26:27], -1, 0
	s_cmp_lt_i32 s13, 2
	s_cselect_b64 s[38:39], -1, 0
	s_waitcnt vmcnt(0)
	v_lshlrev_b32_e32 v0, 2, v36
	v_ashrrev_i32_e32 v32, 4, v36
	v_and_b32_e32 v33, 60, v0
	v_readlane_b32 s64, v249, 30
	s_lshl_b32 s9, s1, 9
	s_and_b64 s[36:37], s[26:27], s[38:39]
	v_or_b32_e32 v220, s5, v33
	v_readlane_b32 s66, v249, 32
	v_readlane_b32 s67, v249, 33
	v_subrev_u32_e32 v0, s9, v32
	v_cndmask_b32_e64 v1, 0, 1, s[36:37]
	v_lshl_add_u64 v[8:9], v[220:221], 2, s[66:67]
	v_cmp_ne_u32_e64 s[0:1], 1, v1
	s_andn2_b64 vcc, exec, s[36:37]
	v_add_u32_e32 v34, s3, v0
	v_readlane_b32 s65, v249, 31
	v_readlane_b32 s68, v249, 34
	v_readlane_b32 s69, v249, 35
	v_readlane_b32 s70, v249, 36
	v_readlane_b32 s71, v249, 37
	v_readlane_b32 s72, v249, 38
	v_readlane_b32 s73, v249, 39
	v_readlane_b32 s74, v249, 40
	v_readlane_b32 s75, v249, 41
	v_readlane_b32 s76, v249, 42
	v_readlane_b32 s77, v249, 43
	v_readlane_b32 s78, v249, 44
	v_readlane_b32 s79, v249, 45
	s_cbranch_vccnz .LBB0_159
	s_movk_i32 s15, 0xc00
	v_mad_i64_i32 v[0:1], s[36:37], v34, s15, v[8:9]
	global_load_dwordx4 v[28:31], v[0:1], off nt
	s_branch .LBB0_160

; DI void conv_job(const float* src0, const float* src1, int ld, int K, int N, bf16_t* dst, int kind, const float* kscale, char* smem, int& rot) {
;     ...
;     float4 v[4][2];
; #pragma unroll
;     for (int q = 0; q < 4; ++q)
; #pragma unroll
;       for (int ps = 0; ps < 2; ++ps) {
;         v[q][ps] = make_float4(0.f, 0.f, 0.f, 0.f);
;         if (q < nkt && col >= 0) { const int k = (kt0 + q) * 64 + ty + 32 * ps; v[q][ps] = *(const float4*)(src + (size_t)k * ld + col); }
;       }
.LBB0_160:
	v_mov_b32_e32 v16, 0
	s_and_b64 vcc, exec, s[0:1]
	v_mov_b32_e32 v17, v16
	v_mov_b32_e32 v18, v16
	v_mov_b32_e32 v19, v16
	s_cbranch_vccnz .LBB0_162
	v_add_u32_e32 v0, 32, v34
	s_movk_i32 s15, 0xc00
	v_mad_i64_i32 v[0:1], s[36:37], v0, s15, v[8:9]
	global_load_dwordx4 v[16:19], v[0:1], off nt
.LBB0_162:
	s_and_b64 vcc, exec, s[0:1]
	s_cbranch_vccnz .LBB0_165
	v_add_u32_e32 v0, 64, v34
	s_movk_i32 s15, 0xc00
	v_mad_i64_i32 v[0:1], s[36:37], v0, s15, v[8:9]
	global_load_dwordx4 v[24:27], v[0:1], off nt
	s_and_b64 vcc, exec, s[0:1]
	s_cbranch_vccz .LBB0_166

; DI void conv_job(const float* src0, const float* src1, int ld, int K, int N, bf16_t* dst, int kind, const float* kscale, char* smem, int& rot) {
;     ...
;     float4 v[4][2];
; #pragma unroll
;     for (int q = 0; q < 4; ++q)
; #pragma unroll
;       for (int ps = 0; ps < 2; ++ps) {
;         v[q][ps] = make_float4(0.f, 0.f, 0.f, 0.f);
;         if (q < nkt && col >= 0) { const int k = (kt0 + q) * 64 + ty + 32 * ps; v[q][ps] = *(const float4*)(src + (size_t)k * ld + col); }
;       }
.LBB0_166:
	v_add_u32_e32 v0, 0x60, v34
	s_movk_i32 s0, 0xc00
	v_mad_i64_i32 v[0:1], s[0:1], v0, s0, v[8:9]
	global_load_dwordx4 v[20:23], v[0:1], off nt
.LBB0_167:
	s_cmp_lt_i32 s13, 1
	s_cselect_b64 s[36:37], -1, 0
	s_and_b64 s[26:27], s[26:27], s[36:37]
	v_cndmask_b32_e64 v0, 0, 1, s[26:27]
	v_cmp_ne_u32_e64 s[0:1], 1, v0
	s_andn2_b64 vcc, exec, s[26:27]
	s_cbranch_vccnz .LBB0_169
	v_add_u32_e32 v0, 0x80, v34
	s_movk_i32 s13, 0xc00
	v_mad_i64_i32 v[0:1], s[26:27], v0, s13, v[8:9]
	global_load_dwordx4 v[12:15], v[0:1], off nt
	s_branch .LBB0_170

; DI void conv_job(const float* src0, const float* src1, int ld, int K, int N, bf16_t* dst, int kind, const float* kscale, char* smem, int& rot) {
;     ...
;     float4 v[4][2];
; #pragma unroll
;     for (int q = 0; q < 4; ++q)
; #pragma unroll
;       for (int ps = 0; ps < 2; ++ps) {
;         v[q][ps] = make_float4(0.f, 0.f, 0.f, 0.f);
;         if (q < nkt && col >= 0) { const int k = (kt0 + q) * 64 + ty + 32 * ps; v[q][ps] = *(const float4*)(src + (size_t)k * ld + col); }
;       }
.LBB0_170:
	v_mov_b32_e32 v0, 0
	s_and_b64 vcc, exec, s[0:1]
	v_mov_b32_e32 v4, 0
	v_mov_b32_e32 v5, 0
	v_mov_b32_e32 v6, 0
	v_mov_b32_e32 v7, 0
	s_cbranch_vccnz .LBB0_172
	v_add_u32_e32 v1, 0xa0, v34
	s_movk_i32 s13, 0xc00
	v_mad_i64_i32 v[2:3], s[26:27], v1, s13, v[8:9]
	global_load_dwordx4 v[4:7], v[2:3], off nt
.LBB0_172:
	s_and_b64 vcc, exec, s[0:1]
	v_mov_b32_e32 v1, 0
	v_mov_b32_e32 v2, 0
	v_mov_b32_e32 v3, 0
	s_cbranch_vccnz .LBB0_174
	v_add_u32_e32 v0, 0xc0, v34
	s_movk_i32 s13, 0xc00
	v_mad_i64_i32 v[0:1], s[26:27], v0, s13, v[8:9]
	global_load_dwordx4 v[0:3], v[0:1], off nt
.LBB0_174:
	s_and_b64 vcc, exec, s[0:1]
	s_cbranch_vccnz .LBB0_176
	v_add_u32_e32 v10, 0xe0, v34
	s_movk_i32 s0, 0xc00
	v_mad_i64_i32 v[8:9], s[0:1], v10, s0, v[8:9]
	global_load_dwordx4 v[8:11], v[8:9], off nt
	s_branch .LBB0_177

; #define MEMBAR() asm volatile("" ::: "memory")
;   DI void operator()(const acc_t& acc, const Unit& u, int wr, int wc, int fr, int fq) const {
;     ...
;     for (int q = 0; q < 4; ++q) {
;       const int ai = q >> 1, mh = q & 1;
;       MEMBAR();
;       f32x4 xv[2][2][2];
; #pragma unroll
;       for (int mm = 0; mm < 2; ++mm) { const int t = row0 + ai * HALF + (2 * mh + mm) * 16;
;         const float* xi = from_input ? xrow_in(p, t) : xrow_ws(p, t);
; #pragma unroll
;         for (int bj = 0; bj < 2; ++bj)
; #pragma unroll
;           for (int n = 0; n < 2; ++n) xv[mm][bj][n] = *(const f32x4*)(xi + col0 + bj * HALF + n * 16); }
;       MEMBAR();
; #pragma unroll
;       for (int mm = 0; mm < 2; ++mm) { const int t = row0 + ai * HALF + (2 * mh + mm) * 16;
;         float* xo = xrow_ws(p, t);
; #pragma unroll
;         for (int bj = 0; bj < 2; ++bj)
; #pragma unroll
;           for (int n = 0; n < 2; ++n) *(f32x4*)(xo + col0 + bj * HALF + n * 16) = xv[mm][bj][n] + gv[bj][n] * acc[ai][bj][2 * mh + mm][n]; }
;     }
.LBB0_1694:
	v_ashrrev_i32_e32 v51, 31, v50
	v_cndmask_b32_e64 v56, 24, 20, s[0:1]
	v_lshlrev_b64 v[62:63], v56, v[50:51]
	v_lshl_add_u64 v[50:51], v[54:55], 0, v[62:63]
	v_lshlrev_b64 v[84:85], 12, v[52:53]
	v_lshl_add_u64 v[50:51], v[50:51], 0, v[84:85]
	v_lshl_add_u64 v[80:81], v[50:51], 0, v[170:171]
	global_load_dwordx4 v[50:53], v[80:81], off nt
	global_load_dwordx4 v[54:57], v[80:81], off offset:64 nt
	global_load_dwordx4 v[58:61], v[80:81], off offset:512 nt
	s_nop 0
	global_load_dwordx4 v[80:83], v[80:81], off offset:576 nt
	v_add_u32_e32 v87, 0xa0, v188
	v_mul_hi_i32 v86, v87, s51
	v_lshrrev_b32_e32 v88, 31, v86
	v_ashrrev_i32_e32 v86, 11, v86
	v_add_u32_e32 v86, v86, v88
	v_mad_i32_i24 v90, v86, s4, v87
	v_cmp_gt_i32_e32 vcc, s50, v90
	v_add_u32_e32 v92, 0xffffff00, v90
	v_mov_b32_e32 v88, s93
	v_mov_b32_e32 v89, s83
	v_ashrrev_i32_e32 v87, 31, v86
	v_ashrrev_i32_e32 v91, 31, v90
	v_cndmask_b32_e32 v89, v88, v89, vcc
	v_mov_b32_e32 v88, s92
	v_mov_b32_e32 v93, s29
	v_cndmask_b32_e32 v90, v92, v90, vcc
	v_cndmask_b32_e64 v92, 24, 20, vcc
	v_cndmask_b32_e32 v88, v88, v93, vcc
	v_cndmask_b32_e32 v91, 0, v91, vcc
	v_lshlrev_b64 v[86:87], v92, v[86:87]
	v_lshl_add_u64 v[86:87], v[88:89], 0, v[86:87]
	v_lshlrev_b64 v[88:89], 12, v[90:91]
	v_lshl_add_u64 v[86:87], v[86:87], 0, v[88:89]
	v_lshl_add_u64 v[86:87], v[86:87], 0, v[170:171]
	s_waitcnt vmcnt(0)
	v_pk_fma_f32 v[10:11], v[10:11], v[66:67], v[34:35]
	v_pk_fma_f32 v[8:9], v[8:9], v[64:65], v[32:33]
	global_store_dwordx4 v[86:87], v[8:11], off offset:576
	v_pk_fma_f32 v[18:19], v[18:19], v[70:71], v[38:39]
	v_pk_fma_f32 v[16:17], v[16:17], v[68:69], v[36:37]
	v_lshl_add_u64 v[8:9], v[48:49], 0, v[62:63]
	v_lshl_add_u64 v[8:9], v[8:9], 0, v[84:85]
	v_pk_fma_f32 v[30:31], v[30:31], v[78:79], v[46:47]
	v_pk_fma_f32 v[28:29], v[28:29], v[76:77], v[44:45]
	v_pk_fma_f32 v[26:27], v[26:27], v[74:75], v[42:43]
	v_pk_fma_f32 v[24:25], v[24:25], v[72:73], v[40:41]
	global_store_dwordx4 v[86:87], v[16:19], off offset:512
	s_mov_b64 s[46:47], s[88:89]
	v_readlane_b32 s88, v254, 43
	v_lshl_add_u64 v[16:17], v[8:9], 0, v[170:171]
	global_store_dwordx4 v[86:87], v[28:31], off
	global_store_dwordx4 v[86:87], v[24:27], off offset:64
	s_and_b64 vcc, exec, s[36:37]
	s_mov_b32 s42, s40
	s_mov_b32 s4, s3
	s_mov_b64 s[90:91], s[44:45]
	v_readlane_b32 s89, v254, 44
	v_pk_fma_f32 v[10:11], v[22:23], v[78:79], v[52:53]
	v_pk_fma_f32 v[8:9], v[20:21], v[76:77], v[50:51]
	global_store_dwordx4 v[16:17], v[8:11], off
	v_pk_fma_f32 v[6:7], v[6:7], v[70:71], v[60:61]
	v_pk_fma_f32 v[4:5], v[4:5], v[68:69], v[58:59]
	v_pk_fma_f32 v[10:11], v[14:15], v[74:75], v[56:57]
	v_pk_fma_f32 v[8:9], v[12:13], v[72:73], v[54:55]
	v_pk_fma_f32 v[2:3], v[2:3], v[66:67], v[82:83]
	v_pk_fma_f32 v[0:1], v[0:1], v[64:65], v[80:81]
	global_store_dwordx4 v[16:17], v[8:11], off offset:64
	global_store_dwordx4 v[16:17], v[4:7], off offset:512
	global_store_dwordx4 v[16:17], v[0:3], off offset:576
	s_cbranch_vccnz .LBB0_1734

; #define PG8_STAGE(bufoff, gbase, voff) do { _Pragma("unroll") for (int _i = 0; _i < 2; ++_i) \
;     __builtin_amdgcn_global_load_lds((const unsigned*)((const char*)(gbase) + (voff)[_i]), (LAS unsigned*)(lds + (bufoff) + ldsw + _i * 8192), 16, 0, 0); } while (0)
; #define PG8_LDA(dst, b, h) do { _Pragma("unroll") for (int m = 0; m < 4; ++m) _Pragma("unroll") for (int k = 0; k < 2; ++k) dst[m][k] = *(const LAS bf16x8*)(lds + PG8_SA(b, h) + aoff + m * 2048 + k * 1024); } while (0)
; #define PG8_LDB(dst, b, h) do { _Pragma("unroll") for (int n = 0; n < 2; ++n) _Pragma("unroll") for (int k = 0; k < 2; ++k) dst[n][k] = *(const LAS bf16x8*)(lds + PG8_SB(b, h) + boff + n * 2048 + k * 1024); } while (0)
; #define PG8_MMA(ai, bj, At, Bt_) do { __builtin_amdgcn_s_setprio(1); _Pragma("unroll") for (int m = 0; m < 4; ++m) _Pragma("unroll") for (int n = 0; n < 2; ++n) _Pragma("unroll") for (int k = 0; k < 2; ++k) \
;     acc[ai][bj][m][n] = __builtin_amdgcn_mfma_f32_16x16x32_bf16(Bt_[n][k], At[m][k], acc[ai][bj][m][n], 0, 0, 0); __builtin_amdgcn_s_setprio(0); } while (0)
; #define PG8_WAIT_V(n) asm volatile("s_waitcnt vmcnt(" #n ")" ::: "memory")
; #define PG8_WAIT_L(n) asm volatile("s_waitcnt lgkmcnt(" #n ")" ::: "memory")
; #define PG8_BAR __builtin_amdgcn_s_barrier()
; #define PG8_SCHED __builtin_amdgcn_sched_barrier(0)
; #define PG8_LDA(dst, b, h) do { _Pragma("unroll") for (int m = 0; m < 4; ++m) _Pragma("unroll") for (int k = 0; k < 2; ++k) dst[m][k] = *(const LAS bf16x8*)(lds + PG8_SA(b, h) + aoff + m * 2048 + k * 1024); } while (0)
; #define PG8_WAIT_V(n) asm volatile("s_waitcnt vmcnt(" #n ")" ::: "memory")
; template <class Epi>
; DI void gemm_phase(char* smem, const bf16_t* A, int lda, const bf16_t* Bt, int ldb, int K, const Order& S_, const Epi& E) {
;     ...
;       PG8_LDB(B0, 0, 0); PG8_SCHED; PG8_LDA(At, 0, 0); PG8_STAGE(PG8_SA(1, 1), a1 + hstepA, voffA);
;       PG8_WAIT_L(8); PG8_BAR; PG8_WAIT_L(0); PG8_MMA(0, 0, At, B0); PG8_BAR; PG8_SCHED;
;       PG8_LDB(B1, 0, 1); PG8_STAGE(PG8_SB(0, 0), b2, voffB);
;       PG8_BAR; PG8_WAIT_L(0); PG8_MMA(0, 1, At, B1); PG8_BAR;
;       PG8_LDA(At, 0, 1); PG8_STAGE(PG8_SA(0, 0), a2, voffA);
;       PG8_BAR; PG8_WAIT_L(0); PG8_MMA(1, 0, At, B0); PG8_BAR; PG8_SCHED;
;       PG8_STAGE(PG8_SB(0, 1), b2 + hstepB, voffB);
;       PG8_WAIT_V(6); PG8_BAR; PG8_MMA(1, 1, At, B1); PG8_BAR;
.LBB0_1701:
	s_add_u32 s0, s90, 0x100
	s_addc_u32 s1, s91, 0
	s_add_i32 s41, 0, 0x10000
	v_add_u32_e32 v76, s41, v185
	ds_read_b128 v[64:67], v76
	ds_read_b128 v[68:71], v76 offset:1024
	ds_read_b128 v[72:75], v76 offset:2048
	ds_read_b128 v[76:79], v76 offset:3072
	s_cmp_eq_u32 s29, 12
	s_cselect_b32 s51, s45, s1
	s_cselect_b32 s50, s44, s0
	s_cselect_b32 s47, s5, s20
	s_cselect_b32 s46, s15, s16
	v_lshl_add_u64 v[182:183], s[90:91], 0, v[166:167]
	s_add_i32 m0, s27, 0xc000
	ds_read_b128 v[144:147], v187
	ds_read_b128 v[148:151], v187 offset:1024
	ds_read_b128 v[152:155], v187 offset:2048
	ds_read_b128 v[156:159], v187 offset:3072
	ds_read_b128 v[170:173], v187 offset:4096
	ds_read_b128 v[174:177], v187 offset:5120
	ds_read_b128 v[178:181], v187 offset:6144
	ds_read_b128 v[188:191], v187 offset:7168
	global_load_lds_dwordx4 v[182:183], off
	v_lshl_add_u64 v[182:183], s[90:91], 0, v[168:169]
	s_add_i32 m0, s27, 0xe000
	s_nop 0
	global_load_lds_dwordx4 v[182:183], off
	s_waitcnt lgkmcnt(8)
	s_barrier
	s_waitcnt lgkmcnt(0)
	s_setprio 1
	s_waitcnt lgkmcnt(0)
	v_mfma_f32_16x16x32_bf16 v[140:143], v[64:67], v[144:147], v[140:143]
	v_mfma_f32_16x16x32_bf16 v[136:139], v[72:75], v[144:147], v[136:139]
	v_mfma_f32_16x16x32_bf16 v[132:135], v[64:67], v[152:155], v[132:135]
	v_mfma_f32_16x16x32_bf16 v[124:127], v[72:75], v[152:155], v[124:127]
	v_mfma_f32_16x16x32_bf16 v[108:111], v[64:67], v[170:173], v[108:111]
	v_mfma_f32_16x16x32_bf16 v[104:107], v[72:75], v[170:173], v[104:107]
	v_mfma_f32_16x16x32_bf16 v[100:103], v[64:67], v[178:181], v[100:103]
	v_mfma_f32_16x16x32_bf16 v[92:95], v[72:75], v[178:181], v[92:95]
	v_mfma_f32_16x16x32_bf16 v[140:143], v[68:71], v[148:151], v[140:143]
	v_mfma_f32_16x16x32_bf16 v[136:139], v[76:79], v[148:151], v[136:139]
	v_mfma_f32_16x16x32_bf16 v[132:135], v[68:71], v[156:159], v[132:135]
	v_mfma_f32_16x16x32_bf16 v[124:127], v[76:79], v[156:159], v[124:127]
	v_mfma_f32_16x16x32_bf16 v[108:111], v[68:71], v[174:177], v[108:111]
	v_mfma_f32_16x16x32_bf16 v[104:107], v[76:79], v[174:177], v[104:107]
	v_mfma_f32_16x16x32_bf16 v[100:103], v[68:71], v[188:191], v[100:103]
	v_mfma_f32_16x16x32_bf16 v[92:95], v[76:79], v[188:191], v[92:95]
	s_setprio 0
	s_barrier
	s_add_i32 s43, 0, 0x14000
	v_add_u32_e32 v182, s43, v185
	s_add_i32 s41, s41, s26
	ds_read_b128 v[210:213], v182
	ds_read_b128 v[214:217], v182 offset:1024
	ds_read_b128 v[234:237], v182 offset:2048
	ds_read_b128 v[238:241], v182 offset:3072
	v_lshl_add_u64 v[182:183], s[46:47], 0, v[220:221]
	s_mov_b32 m0, s41
	v_lshl_add_u64 v[194:195], s[46:47], 0, v[164:165]
	global_load_lds_dwordx4 v[182:183], off
	s_add_i32 m0, s41, 0x2000
	s_nop 0
	global_load_lds_dwordx4 v[194:195], off
	s_barrier
	s_waitcnt lgkmcnt(0)
	s_setprio 1
	s_waitcnt lgkmcnt(0)
	v_mfma_f32_16x16x32_bf16 v[128:131], v[210:213], v[144:147], v[128:131]
	v_mfma_f32_16x16x32_bf16 v[120:123], v[234:237], v[144:147], v[120:123]
	v_mfma_f32_16x16x32_bf16 v[116:119], v[210:213], v[152:155], v[116:119]
	v_mfma_f32_16x16x32_bf16 v[112:115], v[234:237], v[152:155], v[112:115]
	v_mfma_f32_16x16x32_bf16 v[96:99], v[210:213], v[170:173], v[96:99]
	v_mfma_f32_16x16x32_bf16 v[88:91], v[234:237], v[170:173], v[88:91]
	v_mfma_f32_16x16x32_bf16 v[84:87], v[210:213], v[178:181], v[84:87]
	v_mfma_f32_16x16x32_bf16 v[80:83], v[234:237], v[178:181], v[80:83]
	v_mfma_f32_16x16x32_bf16 v[128:131], v[214:217], v[148:151], v[128:131]
	v_mfma_f32_16x16x32_bf16 v[120:123], v[238:241], v[148:151], v[120:123]
	v_mfma_f32_16x16x32_bf16 v[116:119], v[214:217], v[156:159], v[116:119]
	v_mfma_f32_16x16x32_bf16 v[112:115], v[238:241], v[156:159], v[112:115]
	v_mfma_f32_16x16x32_bf16 v[96:99], v[214:217], v[174:177], v[96:99]
	v_mfma_f32_16x16x32_bf16 v[88:91], v[238:241], v[174:177], v[88:91]
	v_mfma_f32_16x16x32_bf16 v[84:87], v[214:217], v[188:191], v[84:87]
	v_mfma_f32_16x16x32_bf16 v[80:83], v[238:241], v[188:191], v[80:83]
	s_setprio 0
	s_mov_b32 m0, s27
	v_lshl_add_u64 v[200:201], s[50:51], 0, v[160:161]
	s_barrier
	ds_read_b128 v[144:147], v187 offset:16384
	ds_read_b128 v[148:151], v187 offset:17408
	ds_read_b128 v[152:155], v187 offset:18432
	ds_read_b128 v[156:159], v187 offset:19456
	ds_read_b128 v[170:173], v187 offset:20480
	ds_read_b128 v[174:177], v187 offset:21504
	ds_read_b128 v[178:181], v187 offset:22528
	ds_read_b128 v[188:191], v187 offset:23552
	global_load_lds_dwordx4 v[200:201], off
	v_lshl_add_u64 v[202:203], s[50:51], 0, v[162:163]
	s_mov_b32 m0, s33
	s_nop 0
	global_load_lds_dwordx4 v[202:203], off
	s_barrier
	s_waitcnt lgkmcnt(0)
	s_setprio 1
	s_waitcnt lgkmcnt(0)
	v_mfma_f32_16x16x32_bf16 v[60:63], v[64:67], v[144:147], v[60:63]
	v_mfma_f32_16x16x32_bf16 v[56:59], v[72:75], v[144:147], v[56:59]
	v_mfma_f32_16x16x32_bf16 v[52:55], v[64:67], v[152:155], v[52:55]
	v_mfma_f32_16x16x32_bf16 v[44:47], v[72:75], v[152:155], v[44:47]
	v_mfma_f32_16x16x32_bf16 v[28:31], v[64:67], v[170:173], v[28:31]
	v_mfma_f32_16x16x32_bf16 v[24:27], v[72:75], v[170:173], v[24:27]
	v_mfma_f32_16x16x32_bf16 v[20:23], v[64:67], v[178:181], v[20:23]
	v_mfma_f32_16x16x32_bf16 v[12:15], v[72:75], v[178:181], v[12:15]
	v_mfma_f32_16x16x32_bf16 v[60:63], v[68:71], v[148:151], v[60:63]
	v_mfma_f32_16x16x32_bf16 v[56:59], v[76:79], v[148:151], v[56:59]
	v_mfma_f32_16x16x32_bf16 v[52:55], v[68:71], v[156:159], v[52:55]
	v_mfma_f32_16x16x32_bf16 v[44:47], v[76:79], v[156:159], v[44:47]
	v_mfma_f32_16x16x32_bf16 v[28:31], v[68:71], v[174:177], v[28:31]
	v_mfma_f32_16x16x32_bf16 v[24:27], v[76:79], v[174:177], v[24:27]
	v_mfma_f32_16x16x32_bf16 v[20:23], v[68:71], v[188:191], v[20:23]
	v_mfma_f32_16x16x32_bf16 v[12:15], v[76:79], v[188:191], v[12:15]
	s_setprio 0
	s_barrier
; #define PG8_STAGE(bufoff, gbase, voff) do { _Pragma("unroll") for (int _i = 0; _i < 2; ++_i) \
;     __builtin_amdgcn_global_load_lds((const unsigned*)((const char*)(gbase) + (voff)[_i]), (LAS unsigned*)(lds + (bufoff) + ldsw + _i * 8192), 16, 0, 0); } while (0)
; #define PG8_LDA(dst, b, h) do { _Pragma("unroll") for (int m = 0; m < 4; ++m) _Pragma("unroll") for (int k = 0; k < 2; ++k) dst[m][k] = *(const LAS bf16x8*)(lds + PG8_SA(b, h) + aoff + m * 2048 + k * 1024); } while (0)
; #define PG8_LDB(dst, b, h) do { _Pragma("unroll") for (int n = 0; n < 2; ++n) _Pragma("unroll") for (int k = 0; k < 2; ++k) dst[n][k] = *(const LAS bf16x8*)(lds + PG8_SB(b, h) + boff + n * 2048 + k * 1024); } while (0)
; #define PG8_MMA(ai, bj, At, Bt_) do { __builtin_amdgcn_s_setprio(1); _Pragma("unroll") for (int m = 0; m < 4; ++m) _Pragma("unroll") for (int n = 0; n < 2; ++n) _Pragma("unroll") for (int k = 0; k < 2; ++k) \
;     acc[ai][bj][m][n] = __builtin_amdgcn_mfma_f32_16x16x32_bf16(Bt_[n][k], At[m][k], acc[ai][bj][m][n], 0, 0, 0); __builtin_amdgcn_s_setprio(0); } while (0)
; #define PG8_WAIT_V(n) asm volatile("s_waitcnt vmcnt(" #n ")" ::: "memory")
; #define PG8_WAIT_L(n) asm volatile("s_waitcnt lgkmcnt(" #n ")" ::: "memory")
; #define PG8_BAR __builtin_amdgcn_s_barrier()
; #define PG8_SCHED __builtin_amdgcn_sched_barrier(0)
; #define PG8_WAIT_V(n) asm volatile("s_waitcnt vmcnt(" #n ")" ::: "memory")
; #define PG8_WAIT_L(n) asm volatile("s_waitcnt lgkmcnt(" #n ")" ::: "memory")
; #define PG8_BAR __builtin_amdgcn_s_barrier()
; template <class Epi>
; DI void gemm_phase(char* smem, const bf16_t* A, int lda, const bf16_t* Bt, int ldb, int K, const Order& S_, const Epi& E) {
;     ...
;       PG8_LDA(At, 0, 1); PG8_STAGE(PG8_SA(0, 0), a2, voffA);
;       PG8_BAR; PG8_WAIT_L(0); PG8_MMA(1, 0, At, B0); PG8_BAR; PG8_SCHED;
;       PG8_STAGE(PG8_SB(0, 1), b2 + hstepB, voffB);
;       PG8_WAIT_V(6); PG8_BAR; PG8_MMA(1, 1, At, B1); PG8_BAR;
;       PG8_LDB(B0, 1, 0); PG8_SCHED; PG8_LDA(At, 1, 0); PG8_STAGE(PG8_SA(0, 1), a2 + hstepA, voffA);
;       PG8_WAIT_L(8); PG8_BAR; PG8_WAIT_L(0); PG8_MMA(0, 0, At, B0); PG8_BAR; PG8_SCHED;
;       PG8_LDB(B1, 1, 1); PG8_STAGE(PG8_SB(1, 0), b3, voffB);
;       PG8_BAR; PG8_WAIT_L(0); PG8_MMA(0, 1, At, B1); PG8_BAR;
;       PG8_LDA(At, 1, 1); PG8_STAGE(PG8_SA(1, 0), a3, voffA);
;       PG8_BAR; PG8_WAIT_L(0); PG8_MMA(1, 0, At, B0); PG8_BAR; PG8_SCHED;
	s_add_u32 s52, s46, 0x40000
	s_addc_u32 s53, s47, 0
	s_add_i32 s41, s43, s26
	v_lshl_add_u64 v[64:65], s[52:53], 0, v[220:221]
	s_mov_b32 m0, s41
	s_nop 0
	global_load_lds_dwordx4 v[64:65], off
	v_lshl_add_u64 v[64:65], s[52:53], 0, v[164:165]
	s_add_i32 m0, s41, 0x2000
	s_nop 0
	global_load_lds_dwordx4 v[64:65], off
	s_waitcnt vmcnt(6)
	s_barrier
	s_setprio 1
	v_mfma_f32_16x16x32_bf16 v[48:51], v[210:213], v[144:147], v[48:51]
	v_mfma_f32_16x16x32_bf16 v[40:43], v[234:237], v[144:147], v[40:43]
	v_mfma_f32_16x16x32_bf16 v[36:39], v[210:213], v[152:155], v[36:39]
	v_mfma_f32_16x16x32_bf16 v[32:35], v[234:237], v[152:155], v[32:35]
	v_mfma_f32_16x16x32_bf16 v[16:19], v[210:213], v[170:173], v[16:19]
	v_mfma_f32_16x16x32_bf16 v[8:11], v[234:237], v[170:173], v[8:11]
	v_mfma_f32_16x16x32_bf16 v[4:7], v[210:213], v[178:181], v[4:7]
	v_mfma_f32_16x16x32_bf16 v[0:3], v[234:237], v[178:181], v[0:3]
	v_mfma_f32_16x16x32_bf16 v[48:51], v[214:217], v[148:151], v[48:51]
	v_mfma_f32_16x16x32_bf16 v[40:43], v[238:241], v[148:151], v[40:43]
	v_mfma_f32_16x16x32_bf16 v[36:39], v[214:217], v[156:159], v[36:39]
	v_mfma_f32_16x16x32_bf16 v[32:35], v[238:241], v[156:159], v[32:35]
	v_mfma_f32_16x16x32_bf16 v[16:19], v[214:217], v[174:177], v[16:19]
	v_mfma_f32_16x16x32_bf16 v[8:11], v[238:241], v[174:177], v[8:11]
	v_mfma_f32_16x16x32_bf16 v[4:7], v[214:217], v[188:191], v[4:7]
	v_mfma_f32_16x16x32_bf16 v[0:3], v[238:241], v[188:191], v[0:3]
	s_setprio 0
	s_add_i32 s41, 0, 0x18000
	v_add_u32_e32 v76, s41, v185
	s_barrier
	ds_read_b128 v[64:67], v76
	ds_read_b128 v[68:71], v76 offset:1024
	ds_read_b128 v[72:75], v76 offset:2048
	ds_read_b128 v[76:79], v76 offset:3072
	s_add_u32 s50, s50, 0xb0000
	s_addc_u32 s51, s51, 0
	s_mov_b32 m0, s34
	v_lshl_add_u64 v[208:209], s[50:51], 0, v[160:161]
	ds_read_b128 v[144:147], v187 offset:32768
	ds_read_b128 v[148:151], v187 offset:33792
	ds_read_b128 v[152:155], v187 offset:34816
	ds_read_b128 v[156:159], v187 offset:35840
	ds_read_b128 v[170:173], v187 offset:36864
	ds_read_b128 v[174:177], v187 offset:37888
	ds_read_b128 v[178:181], v187 offset:38912
	ds_read_b128 v[188:191], v187 offset:39936
	global_load_lds_dwordx4 v[208:209], off
	v_lshl_add_u64 v[208:209], s[50:51], 0, v[162:163]
	s_mov_b32 m0, s38
	s_nop 0
	global_load_lds_dwordx4 v[208:209], off
	s_waitcnt lgkmcnt(8)
	s_barrier
	s_waitcnt lgkmcnt(0)
	s_setprio 1
	s_waitcnt lgkmcnt(0)
	v_mfma_f32_16x16x32_bf16 v[140:143], v[64:67], v[144:147], v[140:143]
	v_mfma_f32_16x16x32_bf16 v[136:139], v[72:75], v[144:147], v[136:139]
	v_mfma_f32_16x16x32_bf16 v[132:135], v[64:67], v[152:155], v[132:135]
	v_mfma_f32_16x16x32_bf16 v[124:127], v[72:75], v[152:155], v[124:127]
	v_mfma_f32_16x16x32_bf16 v[108:111], v[64:67], v[170:173], v[108:111]
	v_mfma_f32_16x16x32_bf16 v[104:107], v[72:75], v[170:173], v[104:107]
	v_mfma_f32_16x16x32_bf16 v[100:103], v[64:67], v[178:181], v[100:103]
	v_mfma_f32_16x16x32_bf16 v[92:95], v[72:75], v[178:181], v[92:95]
	v_mfma_f32_16x16x32_bf16 v[140:143], v[68:71], v[148:151], v[140:143]
	v_mfma_f32_16x16x32_bf16 v[136:139], v[76:79], v[148:151], v[136:139]
	v_mfma_f32_16x16x32_bf16 v[132:135], v[68:71], v[156:159], v[132:135]
	v_mfma_f32_16x16x32_bf16 v[124:127], v[76:79], v[156:159], v[124:127]
	v_mfma_f32_16x16x32_bf16 v[108:111], v[68:71], v[174:177], v[108:111]
	v_mfma_f32_16x16x32_bf16 v[104:107], v[76:79], v[174:177], v[104:107]
	v_mfma_f32_16x16x32_bf16 v[100:103], v[68:71], v[188:191], v[100:103]
	v_mfma_f32_16x16x32_bf16 v[92:95], v[76:79], v[188:191], v[92:95]
	s_setprio 0
	s_barrier
	s_add_i32 s43, 0, 0x1c000
	s_add_i32 s41, s41, s26
	v_add_u32_e32 v204, s43, v185
	v_lshl_add_u64 v[182:183], v[182:183], 0, s[58:59]
	s_mov_b32 m0, s41
	ds_read_b128 v[210:213], v204
	ds_read_b128 v[214:217], v204 offset:1024
	ds_read_b128 v[234:237], v204 offset:2048
	ds_read_b128 v[238:241], v204 offset:3072
	global_load_lds_dwordx4 v[182:183], off
	v_lshl_add_u64 v[182:183], v[194:195], 0, s[58:59]
	s_add_i32 m0, s41, 0x2000
	s_nop 0
	global_load_lds_dwordx4 v[182:183], off
	s_barrier
	s_waitcnt lgkmcnt(0)
	s_setprio 1
	s_waitcnt lgkmcnt(0)
	v_mfma_f32_16x16x32_bf16 v[128:131], v[210:213], v[144:147], v[128:131]
	v_mfma_f32_16x16x32_bf16 v[120:123], v[234:237], v[144:147], v[120:123]
	v_mfma_f32_16x16x32_bf16 v[116:119], v[210:213], v[152:155], v[116:119]
	v_mfma_f32_16x16x32_bf16 v[112:115], v[234:237], v[152:155], v[112:115]
	v_mfma_f32_16x16x32_bf16 v[96:99], v[210:213], v[170:173], v[96:99]
	v_mfma_f32_16x16x32_bf16 v[88:91], v[234:237], v[170:173], v[88:91]
	v_mfma_f32_16x16x32_bf16 v[84:87], v[210:213], v[178:181], v[84:87]
	v_mfma_f32_16x16x32_bf16 v[80:83], v[234:237], v[178:181], v[80:83]
	v_mfma_f32_16x16x32_bf16 v[128:131], v[214:217], v[148:151], v[128:131]
	v_mfma_f32_16x16x32_bf16 v[120:123], v[238:241], v[148:151], v[120:123]
	v_mfma_f32_16x16x32_bf16 v[116:119], v[214:217], v[156:159], v[116:119]
	v_mfma_f32_16x16x32_bf16 v[112:115], v[238:241], v[156:159], v[112:115]
	v_mfma_f32_16x16x32_bf16 v[96:99], v[214:217], v[174:177], v[96:99]
	v_mfma_f32_16x16x32_bf16 v[88:91], v[238:241], v[174:177], v[88:91]
	v_mfma_f32_16x16x32_bf16 v[84:87], v[214:217], v[188:191], v[84:87]
	v_mfma_f32_16x16x32_bf16 v[80:83], v[238:241], v[188:191], v[80:83]
	s_setprio 0
	s_mov_b32 m0, s39
	v_lshl_add_u64 v[182:183], v[200:201], 0, s[58:59]
	s_barrier
; #define MEMBAR() asm volatile("" ::: "memory")
; DI float* modp(const Params& p, int layer, int g, int chunk) { return (float*)(p.ws + OFF_MOD) + ((size_t)(layer * 9 + g) * 6 + chunk) * 1024; }
; #define PG8_STAGE(bufoff, gbase, voff) do { _Pragma("unroll") for (int _i = 0; _i < 2; ++_i) \
;     __builtin_amdgcn_global_load_lds((const unsigned*)((const char*)(gbase) + (voff)[_i]), (LAS unsigned*)(lds + (bufoff) + ldsw + _i * 8192), 16, 0, 0); } while (0)
; #define PG8_WAIT_V(n) asm volatile("s_waitcnt vmcnt(" #n ")" ::: "memory")
; #define PG8_BAR __builtin_amdgcn_s_barrier()
; template <class Epi>
; DI void gemm_phase(char* smem, const bf16_t* A, int lda, const bf16_t* Bt, int ldb, int K, const Order& S_, const Epi& E) {
;     ...
;       PG8_WAIT_V(6); PG8_BAR; PG8_MMA(1, 1, At, B1); PG8_BAR;
;       PG8_LDB(B0, 1, 0); PG8_SCHED; PG8_LDA(At, 1, 0); PG8_STAGE(PG8_SA(0, 1), a2 + hstepA, voffA);
;       PG8_WAIT_L(8); PG8_BAR; PG8_WAIT_L(0); PG8_MMA(0, 0, At, B0); PG8_BAR; PG8_SCHED;
;       PG8_LDB(B1, 1, 1); PG8_STAGE(PG8_SB(1, 0), b3, voffB);
;       PG8_BAR; PG8_WAIT_L(0); PG8_MMA(0, 1, At, B1); PG8_BAR;
;       PG8_LDA(At, 1, 1); PG8_STAGE(PG8_SA(1, 0), a3, voffA);
;       PG8_BAR; PG8_WAIT_L(0); PG8_MMA(1, 0, At, B0); PG8_BAR; PG8_SCHED;
;       PG8_STAGE(PG8_SB(1, 1), b3 + hstepB, voffB);
;       PG8_WAIT_V(6); PG8_BAR; PG8_MMA(1, 1, At, B1); PG8_BAR;
;   DI void operator()(const acc_t& acc, const Unit& u, int wr, int wc, int fr, int fq) const {
;     const int row0 = u.pm * BM + wr * 64 + fr, col0 = u.pn * BM + wc * 32 + 4 * fq;
;     const int b = u.pm / 17, g = (u.pm - b * 17) == 0 ? 8 : b;
;     const float* gate = modp(p, layer, g, chunk);
;     f32x4 gv[2][2];
; #pragma unroll
;     for (int bj = 0; bj < 2; ++bj)
; #pragma unroll
;       for (int n = 0; n < 2; ++n) gv[bj][n] = *(const f32x4*)(gate + col0 + bj * HALF + n * 16);
; #pragma unroll
;     for (int q = 0; q < 4; ++q) {
;       const int ai = q >> 1, mh = q & 1;
;       MEMBAR();
;       f32x4 xv[2][2][2];
; #pragma unroll
;       for (int mm = 0; mm < 2; ++mm) { const int t = row0 + ai * HALF + (2 * mh + mm) * 16;
;         const float* xi = from_input ? xrow_in(p, t) : xrow_ws(p, t);
; #pragma unroll
;         for (int bj = 0; bj < 2; ++bj)
; #pragma unroll
;           for (int n = 0; n < 2; ++n) xv[mm][bj][n] = *(const f32x4*)(xi + col0 + bj * HALF + n * 16); }
	ds_read_b128 v[144:147], v187 offset:49152
	ds_read_b128 v[148:151], v187 offset:50176
	ds_read_b128 v[152:155], v187 offset:51200
	ds_read_b128 v[156:159], v187 offset:52224
	ds_read_b128 v[170:173], v187 offset:53248
	ds_read_b128 v[174:177], v187 offset:54272
	ds_read_b128 v[178:181], v187 offset:55296
	ds_read_b128 v[188:191], v187 offset:56320
	global_load_lds_dwordx4 v[182:183], off
	v_lshl_add_u64 v[182:183], v[202:203], 0, s[58:59]
	s_mov_b32 m0, s49
	s_nop 0
	global_load_lds_dwordx4 v[182:183], off
	s_barrier
	s_waitcnt lgkmcnt(0)
	s_setprio 1
	s_waitcnt lgkmcnt(0)
	v_mfma_f32_16x16x32_bf16 v[60:63], v[64:67], v[144:147], v[60:63]
	v_mfma_f32_16x16x32_bf16 v[56:59], v[72:75], v[144:147], v[56:59]
	v_mfma_f32_16x16x32_bf16 v[52:55], v[64:67], v[152:155], v[52:55]
	v_mfma_f32_16x16x32_bf16 v[44:47], v[72:75], v[152:155], v[44:47]
	v_mfma_f32_16x16x32_bf16 v[28:31], v[64:67], v[170:173], v[28:31]
	v_mfma_f32_16x16x32_bf16 v[24:27], v[72:75], v[170:173], v[24:27]
	v_mfma_f32_16x16x32_bf16 v[20:23], v[64:67], v[178:181], v[20:23]
	v_mfma_f32_16x16x32_bf16 v[12:15], v[72:75], v[178:181], v[12:15]
	v_mfma_f32_16x16x32_bf16 v[60:63], v[68:71], v[148:151], v[60:63]
	v_mfma_f32_16x16x32_bf16 v[56:59], v[76:79], v[148:151], v[56:59]
	v_mfma_f32_16x16x32_bf16 v[52:55], v[68:71], v[156:159], v[52:55]
	v_mfma_f32_16x16x32_bf16 v[44:47], v[76:79], v[156:159], v[44:47]
	v_mfma_f32_16x16x32_bf16 v[28:31], v[68:71], v[174:177], v[28:31]
	v_mfma_f32_16x16x32_bf16 v[24:27], v[76:79], v[174:177], v[24:27]
	v_mfma_f32_16x16x32_bf16 v[20:23], v[68:71], v[188:191], v[20:23]
	v_mfma_f32_16x16x32_bf16 v[12:15], v[76:79], v[188:191], v[12:15]
	s_setprio 0
	s_barrier
	s_add_u32 s46, s46, 0x40080
	s_addc_u32 s47, s47, 0
	s_add_i32 s41, s43, s26
	v_lshl_add_u64 v[64:65], s[46:47], 0, v[220:221]
	s_mov_b32 m0, s41
	s_nop 0
	global_load_lds_dwordx4 v[64:65], off
	v_lshl_add_u64 v[64:65], s[46:47], 0, v[164:165]
	s_add_i32 m0, s41, 0x2000
	s_nop 0
	global_load_lds_dwordx4 v[64:65], off
	s_waitcnt vmcnt(6)
	s_barrier
	s_setprio 1
	v_mfma_f32_16x16x32_bf16 v[48:51], v[210:213], v[144:147], v[48:51]
	v_mfma_f32_16x16x32_bf16 v[40:43], v[234:237], v[144:147], v[40:43]
	v_mfma_f32_16x16x32_bf16 v[36:39], v[210:213], v[152:155], v[36:39]
	v_mfma_f32_16x16x32_bf16 v[32:35], v[234:237], v[152:155], v[32:35]
	v_mfma_f32_16x16x32_bf16 v[16:19], v[210:213], v[170:173], v[16:19]
	v_mfma_f32_16x16x32_bf16 v[8:11], v[234:237], v[170:173], v[8:11]
	v_mfma_f32_16x16x32_bf16 v[4:7], v[210:213], v[178:181], v[4:7]
	v_mfma_f32_16x16x32_bf16 v[0:3], v[234:237], v[178:181], v[0:3]
	v_mfma_f32_16x16x32_bf16 v[48:51], v[214:217], v[148:151], v[48:51]
	v_mfma_f32_16x16x32_bf16 v[40:43], v[238:241], v[148:151], v[40:43]
	v_mfma_f32_16x16x32_bf16 v[36:39], v[214:217], v[156:159], v[36:39]
	v_mfma_f32_16x16x32_bf16 v[32:35], v[238:241], v[156:159], v[32:35]
	v_mfma_f32_16x16x32_bf16 v[16:19], v[214:217], v[174:177], v[16:19]
	v_mfma_f32_16x16x32_bf16 v[8:11], v[238:241], v[174:177], v[8:11]
	v_mfma_f32_16x16x32_bf16 v[4:7], v[214:217], v[188:191], v[4:7]
	v_mfma_f32_16x16x32_bf16 v[0:3], v[238:241], v[188:191], v[0:3]
	s_setprio 0
	s_add_i32 s29, s29, 2
	s_add_u32 s16, s16, 0x100
	s_addc_u32 s20, s20, 0
	s_cmp_gt_u32 s29, 13
	s_mov_b64 s[90:91], s[0:1]
	s_barrier
	s_cbranch_scc0 .LBB0_1701
	s_mul_hi_i32 s0, s4, 0x78787879
	s_lshr_b32 s1, s0, 31
	s_ashr_i32 s0, s0, 3
	s_add_i32 s0, s0, s1
	s_mul_i32 s1, s0, 0xffffffef
	s_sub_i32 s5, 0, s4
	s_cmp_lg_u32 s1, s5
	s_cselect_b32 s0, s0, 8
	v_readlane_b32 s1, v254, 59
	s_add_i32 s0, s0, s1
	s_mul_i32 s0, s0, 6
	s_ashr_i32 s1, s0, 31
	s_lshl_b64 s[0:1], s[0:1], 12
	v_readlane_b32 s5, v253, 27
	v_lshl_or_b32 v172, s42, 8, v186
	s_add_u32 s0, s5, s0
	v_readlane_b32 s5, v253, 28
	s_addc_u32 s1, s5, s1
	v_ashrrev_i32_e32 v173, 31, v172
	v_lshl_add_u64 v[64:65], v[172:173], 2, s[0:1]
	global_load_dwordx4 v[76:79], v[64:65], off nt
	global_load_dwordx4 v[72:75], v[64:65], off offset:64 nt
	global_load_dwordx4 v[68:71], v[64:65], off offset:512 nt
	s_nop 0
	global_load_dwordx4 v[64:67], v[64:65], off offset:576 nt
	v_lshl_add_u32 v188, s4, 8, v184
	s_mov_b32 s51, 0x78787879
	v_mul_hi_i32 v144, v188, s51
	v_lshrrev_b32_e32 v145, 31, v144
	v_ashrrev_i32_e32 v144, 11, v144
	v_add_u32_e32 v144, v144, v145
	s_movk_i32 s4, 0xef00
	v_mad_i32_i24 v145, v144, s4, v188
	v_readlane_b32 s90, v254, 51
	s_movk_i32 s50, 0x100
	v_readlane_b32 s91, v254, 52
	v_ashrrev_i32_e32 v146, 31, v145
	v_add_u32_e32 v147, 0xffffff00, v145
	v_cmp_gt_i32_e64 s[0:1], s50, v145
	s_mov_b64 s[42:43], -1
	s_and_b64 vcc, exec, s[90:91]
	v_cndmask_b32_e64 v175, 0, v146, s[0:1]
	v_cndmask_b32_e64 v174, v147, v145, s[0:1]
	v_readlane_b32 s29, v254, 42
	s_cbranch_vccz .LBB0_1704
	v_mov_b32_e32 v145, s93
	v_mov_b32_e32 v146, s83
	v_cndmask_b32_e64 v147, v145, v146, s[0:1]
	v_mov_b32_e32 v145, s92
	v_mov_b32_e32 v146, s29
	v_cndmask_b32_e64 v146, v145, v146, s[0:1]
	s_mov_b64 s[42:43], 0

;   DI void operator()(const acc_t& acc, const Unit& u, int wr, int wc, int fr, int fq) const {
;     ...
;       for (int mm = 0; mm < 2; ++mm) { const int t = row0 + ai * HALF + (2 * mh + mm) * 16;
;         const float* xi = from_input ? xrow_in(p, t) : xrow_ws(p, t);
; #pragma unroll
;         for (int bj = 0; bj < 2; ++bj)
; #pragma unroll
;           for (int n = 0; n < 2; ++n) xv[mm][bj][n] = *(const f32x4*)(xi + col0 + bj * HALF + n * 16); }
.LBB0_1706:
	v_ashrrev_i32_e32 v145, 31, v144
	v_cndmask_b32_e64 v148, 24, 20, s[0:1]
	v_lshlrev_b64 v[178:179], v148, v[144:145]
	v_lshl_add_u64 v[144:145], v[146:147], 0, v[178:179]
	v_lshlrev_b64 v[146:147], 12, v[174:175]
	v_lshl_add_u64 v[144:145], v[144:145], 0, v[146:147]
	v_lshl_add_u64 v[144:145], v[172:173], 2, v[144:145]
	global_load_dwordx4 v[156:159], v[144:145], off nt
	global_load_dwordx4 v[152:155], v[144:145], off offset:64 nt
	global_load_dwordx4 v[148:151], v[144:145], off offset:512 nt
	s_nop 0
	global_load_dwordx4 v[144:147], v[144:145], off offset:576 nt
	v_or_b32_e32 v171, 16, v188
	v_mul_hi_i32 v170, v171, s51
	v_lshrrev_b32_e32 v176, 31, v170
	v_ashrrev_i32_e32 v170, 11, v170
	v_add_u32_e32 v170, v170, v176
	v_mad_i32_i24 v171, v170, s4, v171
	v_ashrrev_i32_e32 v176, 31, v171
	v_add_u32_e32 v177, 0xffffff00, v171
	v_cmp_gt_i32_e64 s[42:43], s50, v171
	s_mov_b64 s[46:47], -1
	s_and_b64 vcc, exec, s[90:91]
	v_cndmask_b32_e64 v181, 0, v176, s[42:43]
	v_cndmask_b32_e64 v180, v177, v171, s[42:43]
	s_cbranch_vccz .LBB0_1708
	v_mov_b32_e32 v171, s93
	v_mov_b32_e32 v176, s83
	v_cndmask_b32_e64 v177, v171, v176, s[42:43]
	v_mov_b32_e32 v171, s92
	v_mov_b32_e32 v176, s29
	v_cndmask_b32_e64 v176, v171, v176, s[42:43]
	s_mov_b64 s[46:47], 0

; #define MEMBAR() asm volatile("" ::: "memory")
;   DI void operator()(const acc_t& acc, const Unit& u, int wr, int wc, int fr, int fq) const {
;     ...
;       for (int mm = 0; mm < 2; ++mm) { const int t = row0 + ai * HALF + (2 * mh + mm) * 16;
;         const float* xi = from_input ? xrow_in(p, t) : xrow_ws(p, t);
; #pragma unroll
;         for (int bj = 0; bj < 2; ++bj)
; #pragma unroll
;           for (int n = 0; n < 2; ++n) xv[mm][bj][n] = *(const f32x4*)(xi + col0 + bj * HALF + n * 16); }
;       MEMBAR();
; #pragma unroll
;       for (int mm = 0; mm < 2; ++mm) { const int t = row0 + ai * HALF + (2 * mh + mm) * 16;
;         float* xo = xrow_ws(p, t);
; #pragma unroll
;         for (int bj = 0; bj < 2; ++bj)
; #pragma unroll
;           for (int n = 0; n < 2; ++n) *(f32x4*)(xo + col0 + bj * HALF + n * 16) = xv[mm][bj][n] + gv[bj][n] * acc[ai][bj][2 * mh + mm][n]; }
;     }
.LBB0_1710:
	v_ashrrev_i32_e32 v171, 31, v170
	v_cndmask_b32_e64 v189, 24, 20, s[42:43]
	v_lshlrev_b64 v[190:191], v189, v[170:171]
	v_lshl_add_u64 v[170:171], v[182:183], 0, v[190:191]
	v_lshlrev_b64 v[194:195], 12, v[180:181]
	v_lshl_add_u64 v[180:181], v[170:171], 0, v[194:195]
	v_lshlrev_b64 v[170:171], 2, v[172:173]
	v_lshl_add_u64 v[200:201], v[180:181], 0, v[170:171]
	global_load_dwordx4 v[180:183], v[200:201], off nt
	global_load_dwordx4 v[210:213], v[200:201], off offset:64 nt
	global_load_dwordx4 v[214:217], v[200:201], off offset:512 nt
	global_load_dwordx4 v[234:237], v[200:201], off offset:576 nt
	v_mov_b32_e32 v189, s93
	v_mov_b32_e32 v200, s83
	v_cndmask_b32_e64 v201, v189, v200, s[0:1]
	v_mov_b32_e32 v189, s92
	v_mov_b32_e32 v200, s29
	v_cndmask_b32_e64 v200, v189, v200, s[0:1]
	v_lshl_add_u64 v[178:179], v[200:201], 0, v[178:179]
	v_lshlrev_b64 v[174:175], 12, v[174:175]
	v_lshl_add_u64 v[174:175], v[178:179], 0, v[174:175]
	v_lshl_add_u64 v[174:175], v[174:175], 0, v[170:171]
	s_waitcnt vmcnt(0)
	v_pk_fma_f32 v[122:123], v[122:123], v[66:67], v[146:147]
	v_pk_fma_f32 v[120:121], v[120:121], v[64:65], v[144:145]
	global_store_dwordx4 v[174:175], v[120:123], off offset:576
	v_pk_fma_f32 v[130:131], v[130:131], v[70:71], v[150:151]
	v_pk_fma_f32 v[128:129], v[128:129], v[68:69], v[148:149]
	v_lshl_add_u64 v[120:121], v[176:177], 0, v[190:191]
	v_lshl_add_u64 v[120:121], v[120:121], 0, v[194:195]
	v_pk_fma_f32 v[142:143], v[142:143], v[78:79], v[158:159]
	v_pk_fma_f32 v[140:141], v[140:141], v[76:77], v[156:157]
	v_pk_fma_f32 v[138:139], v[138:139], v[74:75], v[154:155]
	v_pk_fma_f32 v[136:137], v[136:137], v[72:73], v[152:153]
	global_store_dwordx4 v[174:175], v[128:131], off offset:512
	global_store_dwordx4 v[174:175], v[140:143], off
	global_store_dwordx4 v[174:175], v[136:139], off offset:64
	v_lshl_add_u64 v[128:129], v[120:121], 0, v[170:171]
	s_mov_b64 s[42:43], -1
	s_and_b64 vcc, exec, s[90:91]
	v_pk_fma_f32 v[122:123], v[134:135], v[78:79], v[182:183]
	v_pk_fma_f32 v[120:121], v[132:133], v[76:77], v[180:181]
	global_store_dwordx4 v[128:129], v[120:123], off
	v_pk_fma_f32 v[114:115], v[114:115], v[66:67], v[236:237]
	v_pk_fma_f32 v[112:113], v[112:113], v[64:65], v[234:235]
	global_store_dwordx4 v[128:129], v[112:115], off offset:576
	v_pk_fma_f32 v[122:123], v[126:127], v[74:75], v[212:213]
	v_pk_fma_f32 v[120:121], v[124:125], v[72:73], v[210:211]
	v_or_b32_e32 v113, 32, v188
	v_mul_hi_i32 v112, v113, s51
	v_pk_fma_f32 v[118:119], v[118:119], v[70:71], v[216:217]
	v_pk_fma_f32 v[116:117], v[116:117], v[68:69], v[214:215]
	v_lshrrev_b32_e32 v114, 31, v112
	v_ashrrev_i32_e32 v112, 11, v112
	global_store_dwordx4 v[128:129], v[120:123], off offset:64
	global_store_dwordx4 v[128:129], v[116:119], off offset:512
	v_add_u32_e32 v112, v112, v114
	v_mad_i32_i24 v113, v112, s4, v113
	v_cmp_gt_i32_e64 s[0:1], s50, v113
	v_ashrrev_i32_e32 v114, 31, v113
	v_add_u32_e32 v115, 0xffffff00, v113
	v_cndmask_b32_e64 v129, 0, v114, s[0:1]
	v_cndmask_b32_e64 v128, v115, v113, s[0:1]
	s_cbranch_vccz .LBB0_1712
	v_mov_b32_e32 v113, s93
	v_mov_b32_e32 v114, s83
	v_cndmask_b32_e64 v115, v113, v114, s[0:1]
	v_mov_b32_e32 v113, s92
	v_mov_b32_e32 v114, s29
	v_cndmask_b32_e64 v114, v113, v114, s[0:1]
	s_mov_b64 s[42:43], 0

;   DI void operator()(const acc_t& acc, const Unit& u, int wr, int wc, int fr, int fq) const {
;     ...
;       for (int mm = 0; mm < 2; ++mm) { const int t = row0 + ai * HALF + (2 * mh + mm) * 16;
;         const float* xi = from_input ? xrow_in(p, t) : xrow_ws(p, t);
; #pragma unroll
;         for (int bj = 0; bj < 2; ++bj)
; #pragma unroll
;           for (int n = 0; n < 2; ++n) xv[mm][bj][n] = *(const f32x4*)(xi + col0 + bj * HALF + n * 16); }
.LBB0_1714:
	v_ashrrev_i32_e32 v113, 31, v112
	v_cndmask_b32_e64 v116, 24, 20, s[0:1]
	v_lshlrev_b64 v[132:133], v116, v[112:113]
	v_lshl_add_u64 v[112:113], v[114:115], 0, v[132:133]
	v_lshlrev_b64 v[114:115], 12, v[128:129]
	v_lshl_add_u64 v[112:113], v[112:113], 0, v[114:115]
	v_lshl_add_u64 v[112:113], v[172:173], 2, v[112:113]
	global_load_dwordx4 v[124:127], v[112:113], off nt
	global_load_dwordx4 v[120:123], v[112:113], off offset:64 nt
	global_load_dwordx4 v[116:119], v[112:113], off offset:512 nt
	s_nop 0
	global_load_dwordx4 v[112:115], v[112:113], off offset:576 nt
	v_or_b32_e32 v130, 48, v188
	v_mul_hi_i32 v131, v130, s51
	v_lshrrev_b32_e32 v134, 31, v131
	v_ashrrev_i32_e32 v131, 11, v131
	v_add_u32_e32 v134, v131, v134
	v_mad_i32_i24 v130, v134, s4, v130
	v_ashrrev_i32_e32 v131, 31, v130
	v_add_u32_e32 v135, 0xffffff00, v130
	v_cmp_gt_i32_e64 s[42:43], s50, v130
	s_mov_b64 s[46:47], -1
	s_and_b64 vcc, exec, s[90:91]
	v_cndmask_b32_e64 v137, 0, v131, s[42:43]
	v_cndmask_b32_e64 v136, v135, v130, s[42:43]
	s_cbranch_vccz .LBB0_1716
	v_mov_b32_e32 v130, s93
	v_mov_b32_e32 v131, s83
	v_cndmask_b32_e64 v131, v130, v131, s[42:43]
	v_mov_b32_e32 v130, s92
	v_mov_b32_e32 v135, s29
	v_cndmask_b32_e64 v130, v130, v135, s[42:43]
	s_mov_b64 s[46:47], 0

; #define MEMBAR() asm volatile("" ::: "memory")
;   DI void operator()(const acc_t& acc, const Unit& u, int wr, int wc, int fr, int fq) const {
;     ...
;       for (int mm = 0; mm < 2; ++mm) { const int t = row0 + ai * HALF + (2 * mh + mm) * 16;
;         const float* xi = from_input ? xrow_in(p, t) : xrow_ws(p, t);
; #pragma unroll
;         for (int bj = 0; bj < 2; ++bj)
; #pragma unroll
;           for (int n = 0; n < 2; ++n) xv[mm][bj][n] = *(const f32x4*)(xi + col0 + bj * HALF + n * 16); }
;       MEMBAR();
; #pragma unroll
;       for (int mm = 0; mm < 2; ++mm) { const int t = row0 + ai * HALF + (2 * mh + mm) * 16;
;         float* xo = xrow_ws(p, t);
; #pragma unroll
;         for (int bj = 0; bj < 2; ++bj)
; #pragma unroll
;           for (int n = 0; n < 2; ++n) *(f32x4*)(xo + col0 + bj * HALF + n * 16) = xv[mm][bj][n] + gv[bj][n] * acc[ai][bj][2 * mh + mm][n]; }
;     }
.LBB0_1718:
	v_ashrrev_i32_e32 v135, 31, v134
	v_cndmask_b32_e64 v140, 24, 20, s[42:43]
	v_lshlrev_b64 v[150:151], v140, v[134:135]
	v_lshl_add_u64 v[134:135], v[138:139], 0, v[150:151]
	v_lshlrev_b64 v[152:153], 12, v[136:137]
	v_lshl_add_u64 v[134:135], v[134:135], 0, v[152:153]
	v_lshl_add_u64 v[146:147], v[134:135], 0, v[170:171]
	global_load_dwordx4 v[134:137], v[146:147], off nt
	global_load_dwordx4 v[138:141], v[146:147], off offset:64 nt
	global_load_dwordx4 v[142:145], v[146:147], off offset:512 nt
	s_nop 0
	global_load_dwordx4 v[146:149], v[146:147], off offset:576 nt
	v_mov_b32_e32 v154, s93
	v_mov_b32_e32 v155, s83
	v_cndmask_b32_e64 v155, v154, v155, s[0:1]
	v_mov_b32_e32 v154, s92
	v_mov_b32_e32 v156, s29
	v_cndmask_b32_e64 v154, v154, v156, s[0:1]
	v_lshl_add_u64 v[132:133], v[154:155], 0, v[132:133]
	v_lshlrev_b64 v[128:129], 12, v[128:129]
	v_lshl_add_u64 v[128:129], v[132:133], 0, v[128:129]
	v_lshl_add_u64 v[128:129], v[128:129], 0, v[170:171]
	s_waitcnt vmcnt(0)
	v_pk_fma_f32 v[90:91], v[90:91], v[66:67], v[114:115]
	v_pk_fma_f32 v[88:89], v[88:89], v[64:65], v[112:113]
	global_store_dwordx4 v[128:129], v[88:91], off offset:576
	v_pk_fma_f32 v[110:111], v[110:111], v[78:79], v[126:127]
	v_pk_fma_f32 v[108:109], v[108:109], v[76:77], v[124:125]
	v_lshl_add_u64 v[88:89], v[130:131], 0, v[150:151]
	v_pk_fma_f32 v[98:99], v[98:99], v[70:71], v[118:119]
	v_pk_fma_f32 v[96:97], v[96:97], v[68:69], v[116:117]
	v_lshl_add_u64 v[88:89], v[88:89], 0, v[152:153]
	global_store_dwordx4 v[128:129], v[108:111], off
	v_pk_fma_f32 v[106:107], v[106:107], v[74:75], v[122:123]
	v_pk_fma_f32 v[104:105], v[104:105], v[72:73], v[120:121]
	global_store_dwordx4 v[128:129], v[96:99], off offset:512
	v_add_u32_e32 v108, 0x80, v188
	global_store_dwordx4 v[128:129], v[104:107], off offset:64
	v_lshl_add_u64 v[96:97], v[88:89], 0, v[170:171]
	s_mov_b64 s[42:43], -1
	s_and_b64 vcc, exec, s[90:91]
	v_pk_fma_f32 v[90:91], v[102:103], v[78:79], v[136:137]
	v_pk_fma_f32 v[88:89], v[100:101], v[76:77], v[134:135]
	global_store_dwordx4 v[96:97], v[88:91], off
	v_pk_fma_f32 v[82:83], v[82:83], v[66:67], v[148:149]
	v_pk_fma_f32 v[80:81], v[80:81], v[64:65], v[146:147]
	global_store_dwordx4 v[96:97], v[80:83], off offset:576
	v_pk_fma_f32 v[90:91], v[94:95], v[74:75], v[140:141]
	v_pk_fma_f32 v[88:89], v[92:93], v[72:73], v[138:139]
	v_mul_hi_i32 v80, v108, s51
	v_pk_fma_f32 v[86:87], v[86:87], v[70:71], v[144:145]
	v_pk_fma_f32 v[84:85], v[84:85], v[68:69], v[142:143]
	v_lshrrev_b32_e32 v81, 31, v80
	v_ashrrev_i32_e32 v80, 11, v80
	global_store_dwordx4 v[96:97], v[88:91], off offset:64
	global_store_dwordx4 v[96:97], v[84:87], off offset:512
	v_add_u32_e32 v80, v80, v81
	v_mad_i32_i24 v81, v80, s4, v108
	v_cmp_gt_i32_e64 s[0:1], s50, v81
	v_ashrrev_i32_e32 v82, 31, v81
	v_add_u32_e32 v83, 0xffffff00, v81
	v_cndmask_b32_e64 v97, 0, v82, s[0:1]
	v_cndmask_b32_e64 v96, v83, v81, s[0:1]
	s_cbranch_vccz .LBB0_1720
	v_mov_b32_e32 v81, s93
	v_mov_b32_e32 v82, s83
	v_cndmask_b32_e64 v83, v81, v82, s[0:1]
	v_mov_b32_e32 v81, s92
	v_mov_b32_e32 v82, s29
	v_cndmask_b32_e64 v82, v81, v82, s[0:1]
	s_mov_b64 s[42:43], 0

;   DI void operator()(const acc_t& acc, const Unit& u, int wr, int wc, int fr, int fq) const {
;     ...
;       for (int mm = 0; mm < 2; ++mm) { const int t = row0 + ai * HALF + (2 * mh + mm) * 16;
;         const float* xi = from_input ? xrow_in(p, t) : xrow_ws(p, t);
; #pragma unroll
;         for (int bj = 0; bj < 2; ++bj)
; #pragma unroll
;           for (int n = 0; n < 2; ++n) xv[mm][bj][n] = *(const f32x4*)(xi + col0 + bj * HALF + n * 16); }
.LBB0_1722:
	v_ashrrev_i32_e32 v81, 31, v80
	v_cndmask_b32_e64 v84, 24, 20, s[0:1]
	v_lshlrev_b64 v[100:101], v84, v[80:81]
	v_lshl_add_u64 v[80:81], v[82:83], 0, v[100:101]
	v_lshlrev_b64 v[82:83], 12, v[96:97]
	v_lshl_add_u64 v[80:81], v[80:81], 0, v[82:83]
	v_lshl_add_u64 v[80:81], v[172:173], 2, v[80:81]
	global_load_dwordx4 v[92:95], v[80:81], off nt
	global_load_dwordx4 v[88:91], v[80:81], off offset:64 nt
	global_load_dwordx4 v[84:87], v[80:81], off offset:512 nt
	s_nop 0
	global_load_dwordx4 v[80:83], v[80:81], off offset:576 nt
	v_add_u32_e32 v98, 0x90, v188
	v_mul_hi_i32 v99, v98, s51
	v_lshrrev_b32_e32 v102, 31, v99
	v_ashrrev_i32_e32 v99, 11, v99
	v_add_u32_e32 v102, v99, v102
	v_mad_i32_i24 v98, v102, s4, v98
	v_ashrrev_i32_e32 v99, 31, v98
	v_add_u32_e32 v103, 0xffffff00, v98
	v_cmp_gt_i32_e64 s[42:43], s50, v98
	s_mov_b64 s[46:47], -1
	s_and_b64 vcc, exec, s[90:91]
	v_cndmask_b32_e64 v105, 0, v99, s[42:43]
	v_cndmask_b32_e64 v104, v103, v98, s[42:43]
	s_cbranch_vccz .LBB0_1724
	v_mov_b32_e32 v98, s93
	v_mov_b32_e32 v99, s83
	v_cndmask_b32_e64 v99, v98, v99, s[42:43]
	v_mov_b32_e32 v98, s92
	v_mov_b32_e32 v103, s29
	v_cndmask_b32_e64 v98, v98, v103, s[42:43]
	s_mov_b64 s[46:47], 0

; #define MEMBAR() asm volatile("" ::: "memory")
;   DI void operator()(const acc_t& acc, const Unit& u, int wr, int wc, int fr, int fq) const {
;     ...
;       for (int mm = 0; mm < 2; ++mm) { const int t = row0 + ai * HALF + (2 * mh + mm) * 16;
;         const float* xi = from_input ? xrow_in(p, t) : xrow_ws(p, t);
; #pragma unroll
;         for (int bj = 0; bj < 2; ++bj)
; #pragma unroll
;           for (int n = 0; n < 2; ++n) xv[mm][bj][n] = *(const f32x4*)(xi + col0 + bj * HALF + n * 16); }
;       MEMBAR();
; #pragma unroll
;       for (int mm = 0; mm < 2; ++mm) { const int t = row0 + ai * HALF + (2 * mh + mm) * 16;
;         float* xo = xrow_ws(p, t);
; #pragma unroll
;         for (int bj = 0; bj < 2; ++bj)
; #pragma unroll
;           for (int n = 0; n < 2; ++n) *(f32x4*)(xo + col0 + bj * HALF + n * 16) = xv[mm][bj][n] + gv[bj][n] * acc[ai][bj][2 * mh + mm][n]; }
;     }
.LBB0_1726:
	v_ashrrev_i32_e32 v103, 31, v102
	v_cndmask_b32_e64 v109, 24, 20, s[42:43]
	v_lshlrev_b64 v[122:123], v109, v[102:103]
	v_lshl_add_u64 v[102:103], v[106:107], 0, v[122:123]
	v_lshlrev_b64 v[106:107], 12, v[104:105]
	v_lshl_add_u64 v[102:103], v[102:103], 0, v[106:107]
	v_lshl_add_u64 v[118:119], v[102:103], 0, v[170:171]
	global_load_dwordx4 v[102:105], v[118:119], off nt
	global_load_dwordx4 v[110:113], v[118:119], off offset:64 nt
	global_load_dwordx4 v[114:117], v[118:119], off offset:512 nt
	s_nop 0
	global_load_dwordx4 v[118:121], v[118:119], off offset:576 nt
	v_mov_b32_e32 v109, s93
	v_mov_b32_e32 v124, s83
	v_cndmask_b32_e64 v125, v109, v124, s[0:1]
	v_mov_b32_e32 v109, s92
	v_mov_b32_e32 v124, s29
	v_cndmask_b32_e64 v124, v109, v124, s[0:1]
	v_lshl_add_u64 v[100:101], v[124:125], 0, v[100:101]
	v_lshlrev_b64 v[96:97], 12, v[96:97]
	v_lshl_add_u64 v[96:97], v[100:101], 0, v[96:97]
	v_lshl_add_u64 v[96:97], v[96:97], 0, v[170:171]
	s_waitcnt vmcnt(0)
	v_pk_fma_f32 v[42:43], v[42:43], v[66:67], v[82:83]
	v_pk_fma_f32 v[40:41], v[40:41], v[64:65], v[80:81]
	global_store_dwordx4 v[96:97], v[40:43], off offset:576
	v_pk_fma_f32 v[50:51], v[50:51], v[70:71], v[86:87]
	v_pk_fma_f32 v[48:49], v[48:49], v[68:69], v[84:85]
	v_lshl_add_u64 v[40:41], v[98:99], 0, v[122:123]
	v_lshl_add_u64 v[40:41], v[40:41], 0, v[106:107]
	v_pk_fma_f32 v[62:63], v[62:63], v[78:79], v[94:95]
	v_pk_fma_f32 v[60:61], v[60:61], v[76:77], v[92:93]
	v_pk_fma_f32 v[58:59], v[58:59], v[74:75], v[90:91]
	v_pk_fma_f32 v[56:57], v[56:57], v[72:73], v[88:89]
	global_store_dwordx4 v[96:97], v[48:51], off offset:512
	global_store_dwordx4 v[96:97], v[60:63], off
	global_store_dwordx4 v[96:97], v[56:59], off offset:64
	v_lshl_add_u64 v[48:49], v[40:41], 0, v[170:171]
	s_mov_b64 s[42:43], -1
	s_and_b64 vcc, exec, s[90:91]
	v_pk_fma_f32 v[42:43], v[54:55], v[78:79], v[104:105]
	v_pk_fma_f32 v[40:41], v[52:53], v[76:77], v[102:103]
	global_store_dwordx4 v[48:49], v[40:43], off
	v_pk_fma_f32 v[34:35], v[34:35], v[66:67], v[120:121]
	v_pk_fma_f32 v[32:33], v[32:33], v[64:65], v[118:119]
	global_store_dwordx4 v[48:49], v[32:35], off offset:576
	v_pk_fma_f32 v[42:43], v[46:47], v[74:75], v[112:113]
	v_pk_fma_f32 v[40:41], v[44:45], v[72:73], v[110:111]
	v_or_b32_e32 v33, 32, v108
	v_mul_hi_i32 v32, v33, s51
	v_pk_fma_f32 v[38:39], v[38:39], v[70:71], v[116:117]
	v_pk_fma_f32 v[36:37], v[36:37], v[68:69], v[114:115]
	v_lshrrev_b32_e32 v34, 31, v32
	v_ashrrev_i32_e32 v32, 11, v32
	global_store_dwordx4 v[48:49], v[40:43], off offset:64
	global_store_dwordx4 v[48:49], v[36:39], off offset:512
	v_add_u32_e32 v32, v32, v34
	v_mad_i32_i24 v33, v32, s4, v33
	v_cmp_gt_i32_e64 s[0:1], s50, v33
	v_ashrrev_i32_e32 v34, 31, v33
	v_add_u32_e32 v36, 0xffffff00, v33
	v_cndmask_b32_e64 v35, 0, v34, s[0:1]
	v_cndmask_b32_e64 v34, v36, v33, s[0:1]
	s_cbranch_vccz .LBB0_1728
	v_mov_b32_e32 v33, s93
	v_mov_b32_e32 v36, s83
	v_cndmask_b32_e64 v37, v33, v36, s[0:1]
	v_mov_b32_e32 v33, s92
	v_mov_b32_e32 v36, s29
	v_cndmask_b32_e64 v36, v33, v36, s[0:1]
	s_mov_b64 s[42:43], 0

;   DI void operator()(const acc_t& acc, const Unit& u, int wr, int wc, int fr, int fq) const {
;     ...
;       for (int mm = 0; mm < 2; ++mm) { const int t = row0 + ai * HALF + (2 * mh + mm) * 16;
;         const float* xi = from_input ? xrow_in(p, t) : xrow_ws(p, t);
; #pragma unroll
;         for (int bj = 0; bj < 2; ++bj)
; #pragma unroll
;           for (int n = 0; n < 2; ++n) xv[mm][bj][n] = *(const f32x4*)(xi + col0 + bj * HALF + n * 16); }
.LBB0_1730:
	v_ashrrev_i32_e32 v33, 31, v32
	v_cndmask_b32_e64 v38, 24, 20, s[0:1]
	v_lshlrev_b64 v[32:33], v38, v[32:33]
	v_lshl_add_u64 v[32:33], v[36:37], 0, v[32:33]
	v_lshlrev_b64 v[34:35], 12, v[34:35]
	v_lshl_add_u64 v[32:33], v[32:33], 0, v[34:35]
	v_lshl_add_u64 v[32:33], v[172:173], 2, v[32:33]
	global_load_dwordx4 v[44:47], v[32:33], off nt
	global_load_dwordx4 v[40:43], v[32:33], off offset:64 nt
	global_load_dwordx4 v[36:39], v[32:33], off offset:512 nt
	s_nop 0
	global_load_dwordx4 v[32:35], v[32:33], off offset:576 nt
	v_add_u32_e32 v48, 0xb0, v188
	v_mul_hi_i32 v49, v48, s51
	v_lshrrev_b32_e32 v50, 31, v49
	v_ashrrev_i32_e32 v49, 11, v49
	v_add_u32_e32 v50, v49, v50
	v_mad_i32_i24 v48, v50, s4, v48
	v_ashrrev_i32_e32 v49, 31, v48
	v_add_u32_e32 v51, 0xffffff00, v48
	v_cmp_gt_i32_e64 s[0:1], s50, v48
	s_mov_b64 s[42:43], -1
	s_and_b64 vcc, exec, s[90:91]
	v_cndmask_b32_e64 v53, 0, v49, s[0:1]
	v_cndmask_b32_e64 v52, v51, v48, s[0:1]
	s_cbranch_vccz .LBB0_1732
	v_mov_b32_e32 v48, s93
	v_mov_b32_e32 v49, s83
	v_cndmask_b32_e64 v49, v48, v49, s[0:1]
	v_mov_b32_e32 v48, s92
	v_mov_b32_e32 v51, s29
	v_cndmask_b32_e64 v48, v48, v51, s[0:1]
	s_mov_b64 s[42:43], 0

; #define PG8_STAGE(bufoff, gbase, voff) do { _Pragma("unroll") for (int _i = 0; _i < 2; ++_i) \
;     __builtin_amdgcn_global_load_lds((const unsigned*)((const char*)(gbase) + (voff)[_i]), (LAS unsigned*)(lds + (bufoff) + ldsw + _i * 8192), 16, 0, 0); } while (0)
; #define PG8_LDA(dst, b, h) do { _Pragma("unroll") for (int m = 0; m < 4; ++m) _Pragma("unroll") for (int k = 0; k < 2; ++k) dst[m][k] = *(const LAS bf16x8*)(lds + PG8_SA(b, h) + aoff + m * 2048 + k * 1024); } while (0)
; #define PG8_LDB(dst, b, h) do { _Pragma("unroll") for (int n = 0; n < 2; ++n) _Pragma("unroll") for (int k = 0; k < 2; ++k) dst[n][k] = *(const LAS bf16x8*)(lds + PG8_SB(b, h) + boff + n * 2048 + k * 1024); } while (0)
; #define PG8_MMA(ai, bj, At, Bt_) do { __builtin_amdgcn_s_setprio(1); _Pragma("unroll") for (int m = 0; m < 4; ++m) _Pragma("unroll") for (int n = 0; n < 2; ++n) _Pragma("unroll") for (int k = 0; k < 2; ++k) \
;     acc[ai][bj][m][n] = __builtin_amdgcn_mfma_f32_16x16x32_bf16(Bt_[n][k], At[m][k], acc[ai][bj][m][n], 0, 0, 0); __builtin_amdgcn_s_setprio(0); } while (0)
; #define PG8_WAIT_V(n) asm volatile("s_waitcnt vmcnt(" #n ")" ::: "memory")
; #define PG8_WAIT_L(n) asm volatile("s_waitcnt lgkmcnt(" #n ")" ::: "memory")
; #define PG8_BAR __builtin_amdgcn_s_barrier()
; #define PG8_SCHED __builtin_amdgcn_sched_barrier(0)
; #define PG8_LDA(dst, b, h) do { _Pragma("unroll") for (int m = 0; m < 4; ++m) _Pragma("unroll") for (int k = 0; k < 2; ++k) dst[m][k] = *(const LAS bf16x8*)(lds + PG8_SA(b, h) + aoff + m * 2048 + k * 1024); } while (0)
; #define PG8_WAIT_V(n) asm volatile("s_waitcnt vmcnt(" #n ")" ::: "memory")
; template <class Epi>
; DI void gemm_phase(char* smem, const bf16_t* A, int lda, const bf16_t* Bt, int ldb, int K, const Order& S_, const Epi& E) {
;     ...
;       PG8_LDB(B0, 0, 0); PG8_SCHED; PG8_LDA(At, 0, 0); PG8_STAGE(PG8_SA(1, 1), a1 + hstepA, voffA);
;       PG8_WAIT_L(8); PG8_BAR; PG8_WAIT_L(0); PG8_MMA(0, 0, At, B0); PG8_BAR; PG8_SCHED;
;       PG8_LDB(B1, 0, 1); PG8_STAGE(PG8_SB(0, 0), b2, voffB);
;       PG8_BAR; PG8_WAIT_L(0); PG8_MMA(0, 1, At, B1); PG8_BAR;
;       PG8_LDA(At, 0, 1); PG8_STAGE(PG8_SA(0, 0), a2, voffA);
;       PG8_BAR; PG8_WAIT_L(0); PG8_MMA(1, 0, At, B0); PG8_BAR; PG8_SCHED;
;       PG8_STAGE(PG8_SB(0, 1), b2 + hstepB, voffB);
;       PG8_WAIT_V(6); PG8_BAR; PG8_MMA(1, 1, At, B1); PG8_BAR;
.LBB0_1929:
	s_add_u32 s44, s42, 0x100
	s_addc_u32 s45, s43, 0
	s_add_i32 s57, 0, 0x10000
	v_add_u32_e32 v140, s57, v153
	ds_read_b128 v[128:131], v140
	ds_read_b128 v[132:135], v140 offset:1024
	ds_read_b128 v[136:139], v140 offset:2048
	ds_read_b128 v[140:143], v140 offset:3072
	s_cmp_eq_u32 s56, 40
	s_cselect_b32 s51, s1, s45
	s_cselect_b32 s50, s0, s44
	s_cselect_b32 s47, s41, s53
	s_cselect_b32 s46, s40, s52
	v_lshl_add_u64 v[150:151], s[42:43], 0, v[146:147]
	s_add_i32 m0, s27, 0xc000
	ds_read_b128 v[156:159], v155
	ds_read_b128 v[160:163], v155 offset:1024
	ds_read_b128 v[164:167], v155 offset:2048
	ds_read_b128 v[168:171], v155 offset:3072
	ds_read_b128 v[172:175], v155 offset:4096
	ds_read_b128 v[176:179], v155 offset:5120
	ds_read_b128 v[180:183], v155 offset:6144
	ds_read_b128 v[184:187], v155 offset:7168
	global_load_lds_dwordx4 v[150:151], off
	v_lshl_add_u64 v[150:151], s[42:43], 0, v[148:149]
	s_add_i32 m0, s27, 0xe000
	s_nop 0
	global_load_lds_dwordx4 v[150:151], off
	s_waitcnt lgkmcnt(8)
	s_barrier
	s_waitcnt lgkmcnt(0)
	s_setprio 1
	s_waitcnt lgkmcnt(0)
	v_mfma_f32_16x16x32_bf16 v[124:127], v[128:131], v[156:159], v[124:127]
	v_mfma_f32_16x16x32_bf16 v[120:123], v[136:139], v[156:159], v[120:123]
	v_mfma_f32_16x16x32_bf16 v[116:119], v[128:131], v[164:167], v[116:119]
	v_mfma_f32_16x16x32_bf16 v[108:111], v[136:139], v[164:167], v[108:111]
	v_mfma_f32_16x16x32_bf16 v[92:95], v[128:131], v[172:175], v[92:95]
	v_mfma_f32_16x16x32_bf16 v[88:91], v[136:139], v[172:175], v[88:91]
	v_mfma_f32_16x16x32_bf16 v[84:87], v[128:131], v[180:183], v[84:87]
	v_mfma_f32_16x16x32_bf16 v[80:83], v[136:139], v[180:183], v[80:83]
	v_mfma_f32_16x16x32_bf16 v[124:127], v[132:135], v[160:163], v[124:127]
	v_mfma_f32_16x16x32_bf16 v[120:123], v[140:143], v[160:163], v[120:123]
	v_mfma_f32_16x16x32_bf16 v[116:119], v[132:135], v[168:171], v[116:119]
	v_mfma_f32_16x16x32_bf16 v[108:111], v[140:143], v[168:171], v[108:111]
	v_mfma_f32_16x16x32_bf16 v[92:95], v[132:135], v[176:179], v[92:95]
	v_mfma_f32_16x16x32_bf16 v[88:91], v[140:143], v[176:179], v[88:91]
	v_mfma_f32_16x16x32_bf16 v[84:87], v[132:135], v[184:187], v[84:87]
	v_mfma_f32_16x16x32_bf16 v[80:83], v[140:143], v[184:187], v[80:83]
	s_setprio 0
	s_barrier
	s_add_i32 s60, 0, 0x14000
	v_add_u32_e32 v150, s60, v153
	s_add_i32 s42, s57, s15
	ds_read_b128 v[188:191], v150
	ds_read_b128 v[210:213], v150 offset:1024
	ds_read_b128 v[214:217], v150 offset:2048
	ds_read_b128 v[234:237], v150 offset:3072
	v_lshl_add_u64 v[150:151], s[46:47], 0, v[220:221]
	s_mov_b32 m0, s42
	v_lshl_add_u64 v[194:195], s[46:47], 0, v[144:145]
	global_load_lds_dwordx4 v[150:151], off
	s_add_i32 m0, s42, 0x2000
	s_nop 0
	global_load_lds_dwordx4 v[194:195], off
	s_barrier
	s_waitcnt lgkmcnt(0)
	s_setprio 1
	s_waitcnt lgkmcnt(0)
	v_mfma_f32_16x16x32_bf16 v[112:115], v[188:191], v[156:159], v[112:115]
	v_mfma_f32_16x16x32_bf16 v[104:107], v[214:217], v[156:159], v[104:107]
	v_mfma_f32_16x16x32_bf16 v[100:103], v[188:191], v[164:167], v[100:103]
	v_mfma_f32_16x16x32_bf16 v[96:99], v[214:217], v[164:167], v[96:99]
	v_mfma_f32_16x16x32_bf16 v[76:79], v[188:191], v[172:175], v[76:79]
	v_mfma_f32_16x16x32_bf16 v[72:75], v[214:217], v[172:175], v[72:75]
	v_mfma_f32_16x16x32_bf16 v[68:71], v[188:191], v[180:183], v[68:71]
	v_mfma_f32_16x16x32_bf16 v[64:67], v[214:217], v[180:183], v[64:67]
	v_mfma_f32_16x16x32_bf16 v[112:115], v[210:213], v[160:163], v[112:115]
	v_mfma_f32_16x16x32_bf16 v[104:107], v[234:237], v[160:163], v[104:107]
	v_mfma_f32_16x16x32_bf16 v[100:103], v[210:213], v[168:171], v[100:103]
	v_mfma_f32_16x16x32_bf16 v[96:99], v[234:237], v[168:171], v[96:99]
	v_mfma_f32_16x16x32_bf16 v[76:79], v[210:213], v[176:179], v[76:79]
	v_mfma_f32_16x16x32_bf16 v[72:75], v[234:237], v[176:179], v[72:75]
	v_mfma_f32_16x16x32_bf16 v[68:71], v[210:213], v[184:187], v[68:71]
	v_mfma_f32_16x16x32_bf16 v[64:67], v[234:237], v[184:187], v[64:67]
	s_setprio 0
	s_mov_b32 m0, s27
	v_lshl_add_u64 v[200:201], s[50:51], 0, v[220:221]
	s_barrier
	ds_read_b128 v[156:159], v155 offset:16384
	ds_read_b128 v[160:163], v155 offset:17408
	ds_read_b128 v[164:167], v155 offset:18432
	ds_read_b128 v[168:171], v155 offset:19456
	ds_read_b128 v[172:175], v155 offset:20480
	ds_read_b128 v[176:179], v155 offset:21504
	ds_read_b128 v[180:183], v155 offset:22528
	ds_read_b128 v[184:187], v155 offset:23552
	global_load_lds_dwordx4 v[200:201], off
	v_lshl_add_u64 v[202:203], s[50:51], 0, v[144:145]
	s_mov_b32 m0, s29
	s_nop 0
	global_load_lds_dwordx4 v[202:203], off
	s_barrier
	s_waitcnt lgkmcnt(0)
	s_setprio 1
	s_waitcnt lgkmcnt(0)
	v_mfma_f32_16x16x32_bf16 v[60:63], v[128:131], v[156:159], v[60:63]
	v_mfma_f32_16x16x32_bf16 v[56:59], v[136:139], v[156:159], v[56:59]
	v_mfma_f32_16x16x32_bf16 v[52:55], v[128:131], v[164:167], v[52:55]
	v_mfma_f32_16x16x32_bf16 v[48:51], v[136:139], v[164:167], v[48:51]
	v_mfma_f32_16x16x32_bf16 v[28:31], v[128:131], v[172:175], v[28:31]
	v_mfma_f32_16x16x32_bf16 v[24:27], v[136:139], v[172:175], v[24:27]
	v_mfma_f32_16x16x32_bf16 v[20:23], v[128:131], v[180:183], v[20:23]
	v_mfma_f32_16x16x32_bf16 v[16:19], v[136:139], v[180:183], v[16:19]
	v_mfma_f32_16x16x32_bf16 v[60:63], v[132:135], v[160:163], v[60:63]
	v_mfma_f32_16x16x32_bf16 v[56:59], v[140:143], v[160:163], v[56:59]
	v_mfma_f32_16x16x32_bf16 v[52:55], v[132:135], v[168:171], v[52:55]
	v_mfma_f32_16x16x32_bf16 v[48:51], v[140:143], v[168:171], v[48:51]
	v_mfma_f32_16x16x32_bf16 v[28:31], v[132:135], v[176:179], v[28:31]
	v_mfma_f32_16x16x32_bf16 v[24:27], v[140:143], v[176:179], v[24:27]
	v_mfma_f32_16x16x32_bf16 v[20:23], v[132:135], v[184:187], v[20:23]
	v_mfma_f32_16x16x32_bf16 v[16:19], v[140:143], v[184:187], v[16:19]
	s_setprio 0
	s_barrier
; #define PG8_STAGE(bufoff, gbase, voff) do { _Pragma("unroll") for (int _i = 0; _i < 2; ++_i) \
;     __builtin_amdgcn_global_load_lds((const unsigned*)((const char*)(gbase) + (voff)[_i]), (LAS unsigned*)(lds + (bufoff) + ldsw + _i * 8192), 16, 0, 0); } while (0)
; #define PG8_LDA(dst, b, h) do { _Pragma("unroll") for (int m = 0; m < 4; ++m) _Pragma("unroll") for (int k = 0; k < 2; ++k) dst[m][k] = *(const LAS bf16x8*)(lds + PG8_SA(b, h) + aoff + m * 2048 + k * 1024); } while (0)
; #define PG8_LDB(dst, b, h) do { _Pragma("unroll") for (int n = 0; n < 2; ++n) _Pragma("unroll") for (int k = 0; k < 2; ++k) dst[n][k] = *(const LAS bf16x8*)(lds + PG8_SB(b, h) + boff + n * 2048 + k * 1024); } while (0)
; #define PG8_MMA(ai, bj, At, Bt_) do { __builtin_amdgcn_s_setprio(1); _Pragma("unroll") for (int m = 0; m < 4; ++m) _Pragma("unroll") for (int n = 0; n < 2; ++n) _Pragma("unroll") for (int k = 0; k < 2; ++k) \
;     acc[ai][bj][m][n] = __builtin_amdgcn_mfma_f32_16x16x32_bf16(Bt_[n][k], At[m][k], acc[ai][bj][m][n], 0, 0, 0); __builtin_amdgcn_s_setprio(0); } while (0)
; #define PG8_WAIT_V(n) asm volatile("s_waitcnt vmcnt(" #n ")" ::: "memory")
; #define PG8_WAIT_L(n) asm volatile("s_waitcnt lgkmcnt(" #n ")" ::: "memory")
; #define PG8_BAR __builtin_amdgcn_s_barrier()
; #define PG8_SCHED __builtin_amdgcn_sched_barrier(0)
; #define PG8_WAIT_V(n) asm volatile("s_waitcnt vmcnt(" #n ")" ::: "memory")
; #define PG8_WAIT_L(n) asm volatile("s_waitcnt lgkmcnt(" #n ")" ::: "memory")
; #define PG8_BAR __builtin_amdgcn_s_barrier()
; template <class Epi>
; DI void gemm_phase(char* smem, const bf16_t* A, int lda, const bf16_t* Bt, int ldb, int K, const Order& S_, const Epi& E) {
;     ...
;       PG8_LDA(At, 0, 1); PG8_STAGE(PG8_SA(0, 0), a2, voffA);
;       PG8_BAR; PG8_WAIT_L(0); PG8_MMA(1, 0, At, B0); PG8_BAR; PG8_SCHED;
;       PG8_STAGE(PG8_SB(0, 1), b2 + hstepB, voffB);
;       PG8_WAIT_V(6); PG8_BAR; PG8_MMA(1, 1, At, B1); PG8_BAR;
;       PG8_LDB(B0, 1, 0); PG8_SCHED; PG8_LDA(At, 1, 0); PG8_STAGE(PG8_SA(0, 1), a2 + hstepA, voffA);
;       PG8_WAIT_L(8); PG8_BAR; PG8_WAIT_L(0); PG8_MMA(0, 0, At, B0); PG8_BAR; PG8_SCHED;
;       PG8_LDB(B1, 1, 1); PG8_STAGE(PG8_SB(1, 0), b3, voffB);
;       PG8_BAR; PG8_WAIT_L(0); PG8_MMA(0, 1, At, B1); PG8_BAR;
;       PG8_LDA(At, 1, 1); PG8_STAGE(PG8_SA(1, 0), a3, voffA);
;       PG8_BAR; PG8_WAIT_L(0); PG8_MMA(1, 0, At, B0); PG8_BAR; PG8_SCHED;
	s_add_u32 s42, s46, 0xb0000
	s_addc_u32 s43, s47, 0
	s_add_i32 s57, s60, s15
	v_lshl_add_u64 v[128:129], s[42:43], 0, v[220:221]
	s_mov_b32 m0, s57
	s_nop 0
	global_load_lds_dwordx4 v[128:129], off
	v_lshl_add_u64 v[128:129], s[42:43], 0, v[144:145]
	s_add_i32 m0, s57, 0x2000
	s_nop 0
	global_load_lds_dwordx4 v[128:129], off
	s_waitcnt vmcnt(6)
	s_barrier
	s_setprio 1
	v_mfma_f32_16x16x32_bf16 v[44:47], v[188:191], v[156:159], v[44:47]
	v_mfma_f32_16x16x32_bf16 v[40:43], v[214:217], v[156:159], v[40:43]
	v_mfma_f32_16x16x32_bf16 v[36:39], v[188:191], v[164:167], v[36:39]
	v_mfma_f32_16x16x32_bf16 v[32:35], v[214:217], v[164:167], v[32:35]
	v_mfma_f32_16x16x32_bf16 v[12:15], v[188:191], v[172:175], v[12:15]
	v_mfma_f32_16x16x32_bf16 v[8:11], v[214:217], v[172:175], v[8:11]
	v_mfma_f32_16x16x32_bf16 v[4:7], v[188:191], v[180:183], v[4:7]
	v_mfma_f32_16x16x32_bf16 v[0:3], v[214:217], v[180:183], v[0:3]
	v_mfma_f32_16x16x32_bf16 v[44:47], v[210:213], v[160:163], v[44:47]
	v_mfma_f32_16x16x32_bf16 v[40:43], v[234:237], v[160:163], v[40:43]
	v_mfma_f32_16x16x32_bf16 v[36:39], v[210:213], v[168:171], v[36:39]
	v_mfma_f32_16x16x32_bf16 v[32:35], v[234:237], v[168:171], v[32:35]
	v_mfma_f32_16x16x32_bf16 v[12:15], v[210:213], v[176:179], v[12:15]
	v_mfma_f32_16x16x32_bf16 v[8:11], v[234:237], v[176:179], v[8:11]
	v_mfma_f32_16x16x32_bf16 v[4:7], v[210:213], v[184:187], v[4:7]
	v_mfma_f32_16x16x32_bf16 v[0:3], v[234:237], v[184:187], v[0:3]
	s_setprio 0
	s_add_i32 s57, 0, 0x18000
	v_add_u32_e32 v140, s57, v153
	s_barrier
	ds_read_b128 v[128:131], v140
	ds_read_b128 v[132:135], v140 offset:1024
	ds_read_b128 v[136:139], v140 offset:2048
	ds_read_b128 v[140:143], v140 offset:3072
	s_add_u32 s42, s50, 0xb0000
	s_addc_u32 s43, s51, 0
	s_mov_b32 m0, s33
	v_lshl_add_u64 v[188:189], s[42:43], 0, v[220:221]
	ds_read_b128 v[156:159], v155 offset:32768
	ds_read_b128 v[160:163], v155 offset:33792
	ds_read_b128 v[164:167], v155 offset:34816
	ds_read_b128 v[168:171], v155 offset:35840
	ds_read_b128 v[172:175], v155 offset:36864
	ds_read_b128 v[176:179], v155 offset:37888
	ds_read_b128 v[180:183], v155 offset:38912
	ds_read_b128 v[184:187], v155 offset:39936
	global_load_lds_dwordx4 v[188:189], off
	v_lshl_add_u64 v[188:189], s[42:43], 0, v[144:145]
	s_mov_b32 m0, s34
	s_nop 0
	global_load_lds_dwordx4 v[188:189], off
	s_waitcnt lgkmcnt(8)
	s_barrier
	s_waitcnt lgkmcnt(0)
	s_setprio 1
	s_waitcnt lgkmcnt(0)
	v_mfma_f32_16x16x32_bf16 v[124:127], v[128:131], v[156:159], v[124:127]
	v_mfma_f32_16x16x32_bf16 v[120:123], v[136:139], v[156:159], v[120:123]
	v_mfma_f32_16x16x32_bf16 v[116:119], v[128:131], v[164:167], v[116:119]
	v_mfma_f32_16x16x32_bf16 v[108:111], v[136:139], v[164:167], v[108:111]
	v_mfma_f32_16x16x32_bf16 v[92:95], v[128:131], v[172:175], v[92:95]
	v_mfma_f32_16x16x32_bf16 v[88:91], v[136:139], v[172:175], v[88:91]
	v_mfma_f32_16x16x32_bf16 v[84:87], v[128:131], v[180:183], v[84:87]
	v_mfma_f32_16x16x32_bf16 v[80:83], v[136:139], v[180:183], v[80:83]
	v_mfma_f32_16x16x32_bf16 v[124:127], v[132:135], v[160:163], v[124:127]
	v_mfma_f32_16x16x32_bf16 v[120:123], v[140:143], v[160:163], v[120:123]
	v_mfma_f32_16x16x32_bf16 v[116:119], v[132:135], v[168:171], v[116:119]
	v_mfma_f32_16x16x32_bf16 v[108:111], v[140:143], v[168:171], v[108:111]
	v_mfma_f32_16x16x32_bf16 v[92:95], v[132:135], v[176:179], v[92:95]
	v_mfma_f32_16x16x32_bf16 v[88:91], v[140:143], v[176:179], v[88:91]
	v_mfma_f32_16x16x32_bf16 v[84:87], v[132:135], v[184:187], v[84:87]
	v_mfma_f32_16x16x32_bf16 v[80:83], v[140:143], v[184:187], v[80:83]
	s_setprio 0
	s_barrier
	s_add_i32 s50, 0, 0x1c000
	s_add_i32 s42, s57, s15
	v_add_u32_e32 v204, s50, v153
	v_lshl_add_u64 v[150:151], v[150:151], 0, s[58:59]
	s_mov_b32 m0, s42
	ds_read_b128 v[188:191], v204
	ds_read_b128 v[210:213], v204 offset:1024
	ds_read_b128 v[214:217], v204 offset:2048
	ds_read_b128 v[234:237], v204 offset:3072
	global_load_lds_dwordx4 v[150:151], off
	v_lshl_add_u64 v[150:151], v[194:195], 0, s[58:59]
	s_add_i32 m0, s42, 0x2000
	s_nop 0
	global_load_lds_dwordx4 v[150:151], off
	s_barrier
	s_waitcnt lgkmcnt(0)
	s_setprio 1
	s_waitcnt lgkmcnt(0)
	v_mfma_f32_16x16x32_bf16 v[112:115], v[188:191], v[156:159], v[112:115]
	v_mfma_f32_16x16x32_bf16 v[104:107], v[214:217], v[156:159], v[104:107]
	v_mfma_f32_16x16x32_bf16 v[100:103], v[188:191], v[164:167], v[100:103]
	v_mfma_f32_16x16x32_bf16 v[96:99], v[214:217], v[164:167], v[96:99]
	v_mfma_f32_16x16x32_bf16 v[76:79], v[188:191], v[172:175], v[76:79]
	v_mfma_f32_16x16x32_bf16 v[72:75], v[214:217], v[172:175], v[72:75]
	v_mfma_f32_16x16x32_bf16 v[68:71], v[188:191], v[180:183], v[68:71]
	v_mfma_f32_16x16x32_bf16 v[64:67], v[214:217], v[180:183], v[64:67]
	v_mfma_f32_16x16x32_bf16 v[112:115], v[210:213], v[160:163], v[112:115]
	v_mfma_f32_16x16x32_bf16 v[104:107], v[234:237], v[160:163], v[104:107]
	v_mfma_f32_16x16x32_bf16 v[100:103], v[210:213], v[168:171], v[100:103]
	v_mfma_f32_16x16x32_bf16 v[96:99], v[234:237], v[168:171], v[96:99]
	v_mfma_f32_16x16x32_bf16 v[76:79], v[210:213], v[176:179], v[76:79]
	v_mfma_f32_16x16x32_bf16 v[72:75], v[234:237], v[176:179], v[72:75]
	v_mfma_f32_16x16x32_bf16 v[68:71], v[210:213], v[184:187], v[68:71]
	v_mfma_f32_16x16x32_bf16 v[64:67], v[234:237], v[184:187], v[64:67]
	s_setprio 0
	s_mov_b32 m0, s38
	v_lshl_add_u64 v[150:151], v[200:201], 0, s[58:59]
	s_barrier
	ds_read_b128 v[156:159], v155 offset:49152
	ds_read_b128 v[160:163], v155 offset:50176
	ds_read_b128 v[164:167], v155 offset:51200
	ds_read_b128 v[168:171], v155 offset:52224
	ds_read_b128 v[172:175], v155 offset:53248
	ds_read_b128 v[176:179], v155 offset:54272
	ds_read_b128 v[180:183], v155 offset:55296
	ds_read_b128 v[184:187], v155 offset:56320
	global_load_lds_dwordx4 v[150:151], off
	v_lshl_add_u64 v[150:151], v[202:203], 0, s[58:59]
	s_mov_b32 m0, s20
	s_nop 0
	global_load_lds_dwordx4 v[150:151], off
	s_barrier
; #define MEMBAR() asm volatile("" ::: "memory")
; DI float* modp(const Params& p, int layer, int g, int chunk) { return (float*)(p.ws + OFF_MOD) + ((size_t)(layer * 9 + g) * 6 + chunk) * 1024; }
; #define PG8_STAGE(bufoff, gbase, voff) do { _Pragma("unroll") for (int _i = 0; _i < 2; ++_i) \
;     __builtin_amdgcn_global_load_lds((const unsigned*)((const char*)(gbase) + (voff)[_i]), (LAS unsigned*)(lds + (bufoff) + ldsw + _i * 8192), 16, 0, 0); } while (0)
; #define PG8_WAIT_V(n) asm volatile("s_waitcnt vmcnt(" #n ")" ::: "memory")
; #define PG8_BAR __builtin_amdgcn_s_barrier()
; template <class Epi>
; DI void gemm_phase(char* smem, const bf16_t* A, int lda, const bf16_t* Bt, int ldb, int K, const Order& S_, const Epi& E) {
;     ...
;       PG8_WAIT_V(6); PG8_BAR; PG8_MMA(1, 1, At, B1); PG8_BAR;
;       PG8_LDB(B0, 1, 0); PG8_SCHED; PG8_LDA(At, 1, 0); PG8_STAGE(PG8_SA(0, 1), a2 + hstepA, voffA);
;       PG8_WAIT_L(8); PG8_BAR; PG8_WAIT_L(0); PG8_MMA(0, 0, At, B0); PG8_BAR; PG8_SCHED;
;       PG8_LDB(B1, 1, 1); PG8_STAGE(PG8_SB(1, 0), b3, voffB);
;       PG8_BAR; PG8_WAIT_L(0); PG8_MMA(0, 1, At, B1); PG8_BAR;
;       PG8_LDA(At, 1, 1); PG8_STAGE(PG8_SA(1, 0), a3, voffA);
;       PG8_BAR; PG8_WAIT_L(0); PG8_MMA(1, 0, At, B0); PG8_BAR; PG8_SCHED;
;       PG8_STAGE(PG8_SB(1, 1), b3 + hstepB, voffB);
;       PG8_WAIT_V(6); PG8_BAR; PG8_MMA(1, 1, At, B1); PG8_BAR;
;   DI void operator()(const acc_t& acc, const Unit& u, int wr, int wc, int fr, int fq) const {
;     const int row0 = u.pm * BM + wr * 64 + fr, col0 = u.pn * BM + wc * 32 + 4 * fq;
;     const int b = u.pm / 17, g = (u.pm - b * 17) == 0 ? 8 : b;
;     const float* gate = modp(p, layer, g, chunk);
;     f32x4 gv[2][2];
; #pragma unroll
;     for (int bj = 0; bj < 2; ++bj)
; #pragma unroll
;       for (int n = 0; n < 2; ++n) gv[bj][n] = *(const f32x4*)(gate + col0 + bj * HALF + n * 16);
; #pragma unroll
;     for (int q = 0; q < 4; ++q) {
;       const int ai = q >> 1, mh = q & 1;
;       MEMBAR();
;       f32x4 xv[2][2][2];
; #pragma unroll
;       for (int mm = 0; mm < 2; ++mm) { const int t = row0 + ai * HALF + (2 * mh + mm) * 16;
;         const float* xi = from_input ? xrow_in(p, t) : xrow_ws(p, t);
; #pragma unroll
;         for (int bj = 0; bj < 2; ++bj)
; #pragma unroll
;           for (int n = 0; n < 2; ++n) xv[mm][bj][n] = *(const f32x4*)(xi + col0 + bj * HALF + n * 16); }
	s_waitcnt lgkmcnt(0)
	s_setprio 1
	s_waitcnt lgkmcnt(0)
	v_mfma_f32_16x16x32_bf16 v[60:63], v[128:131], v[156:159], v[60:63]
	v_mfma_f32_16x16x32_bf16 v[56:59], v[136:139], v[156:159], v[56:59]
	v_mfma_f32_16x16x32_bf16 v[52:55], v[128:131], v[164:167], v[52:55]
	v_mfma_f32_16x16x32_bf16 v[48:51], v[136:139], v[164:167], v[48:51]
	v_mfma_f32_16x16x32_bf16 v[28:31], v[128:131], v[172:175], v[28:31]
	v_mfma_f32_16x16x32_bf16 v[24:27], v[136:139], v[172:175], v[24:27]
	v_mfma_f32_16x16x32_bf16 v[20:23], v[128:131], v[180:183], v[20:23]
	v_mfma_f32_16x16x32_bf16 v[16:19], v[136:139], v[180:183], v[16:19]
	v_mfma_f32_16x16x32_bf16 v[60:63], v[132:135], v[160:163], v[60:63]
	v_mfma_f32_16x16x32_bf16 v[56:59], v[140:143], v[160:163], v[56:59]
	v_mfma_f32_16x16x32_bf16 v[52:55], v[132:135], v[168:171], v[52:55]
	v_mfma_f32_16x16x32_bf16 v[48:51], v[140:143], v[168:171], v[48:51]
	v_mfma_f32_16x16x32_bf16 v[28:31], v[132:135], v[176:179], v[28:31]
	v_mfma_f32_16x16x32_bf16 v[24:27], v[140:143], v[176:179], v[24:27]
	v_mfma_f32_16x16x32_bf16 v[20:23], v[132:135], v[184:187], v[20:23]
	v_mfma_f32_16x16x32_bf16 v[16:19], v[140:143], v[184:187], v[16:19]
	s_setprio 0
	s_barrier
	s_add_u32 s42, s46, 0xb0080
	s_addc_u32 s43, s47, 0
	s_add_i32 s46, s50, s15
	v_lshl_add_u64 v[128:129], s[42:43], 0, v[220:221]
	s_mov_b32 m0, s46
	s_nop 0
	global_load_lds_dwordx4 v[128:129], off
	v_lshl_add_u64 v[128:129], s[42:43], 0, v[144:145]
	s_add_i32 m0, s46, 0x2000
	s_nop 0
	global_load_lds_dwordx4 v[128:129], off
	s_waitcnt vmcnt(6)
	s_barrier
	s_setprio 1
	v_mfma_f32_16x16x32_bf16 v[44:47], v[188:191], v[156:159], v[44:47]
	v_mfma_f32_16x16x32_bf16 v[40:43], v[214:217], v[156:159], v[40:43]
	v_mfma_f32_16x16x32_bf16 v[36:39], v[188:191], v[164:167], v[36:39]
	v_mfma_f32_16x16x32_bf16 v[32:35], v[214:217], v[164:167], v[32:35]
	v_mfma_f32_16x16x32_bf16 v[12:15], v[188:191], v[172:175], v[12:15]
	v_mfma_f32_16x16x32_bf16 v[8:11], v[214:217], v[172:175], v[8:11]
	v_mfma_f32_16x16x32_bf16 v[4:7], v[188:191], v[180:183], v[4:7]
	v_mfma_f32_16x16x32_bf16 v[0:3], v[214:217], v[180:183], v[0:3]
	v_mfma_f32_16x16x32_bf16 v[44:47], v[210:213], v[160:163], v[44:47]
	v_mfma_f32_16x16x32_bf16 v[40:43], v[234:237], v[160:163], v[40:43]
	v_mfma_f32_16x16x32_bf16 v[36:39], v[210:213], v[168:171], v[36:39]
	v_mfma_f32_16x16x32_bf16 v[32:35], v[234:237], v[168:171], v[32:35]
	v_mfma_f32_16x16x32_bf16 v[12:15], v[210:213], v[176:179], v[12:15]
	v_mfma_f32_16x16x32_bf16 v[8:11], v[234:237], v[176:179], v[8:11]
	v_mfma_f32_16x16x32_bf16 v[4:7], v[210:213], v[184:187], v[4:7]
	v_mfma_f32_16x16x32_bf16 v[0:3], v[234:237], v[184:187], v[0:3]
	s_setprio 0
	s_add_i32 s56, s56, 2
	s_add_u32 s52, s52, 0x100
	s_addc_u32 s53, s53, 0
	s_cmp_gt_u32 s56, 41
	s_mov_b64 s[42:43], s[44:45]
	s_barrier
	s_cbranch_scc0 .LBB0_1929
	v_lshl_add_u32 v157, s39, 8, v152
	s_mov_b32 s51, 0x78787879
	v_mul_hi_i32 v156, v157, s51
	v_lshrrev_b32_e32 v158, 31, v156
	v_ashrrev_i32_e32 v156, 11, v156
	v_add_u32_e32 v162, v156, v158
	s_mul_hi_i32 s42, s39, 0x78787879
	v_mad_i32_i24 v161, v162, s80, v157
	s_movk_i32 s50, 0x100
	s_lshr_b32 s43, s42, 31
	s_ashr_i32 s42, s42, 3
	v_ashrrev_i32_e32 v166, 31, v161
	v_add_u32_e32 v168, 0xffffff00, v161
	v_cmp_gt_i32_e32 vcc, s50, v161
	s_add_i32 s42, s42, s43
	v_ashrrev_i32_e32 v163, 31, v162
	v_cndmask_b32_e32 v167, 0, v166, vcc
	v_cndmask_b32_e32 v166, v168, v161, vcc
	v_cndmask_b32_e64 v161, 24, 20, vcc
	s_mul_i32 s43, s42, 0xffffffef
	s_sub_i32 s44, 0, s39
	v_lshlrev_b64 v[162:163], v161, v[162:163]
	v_or_b32_e32 v161, 16, v157
	s_cmp_lg_u32 s43, s44
	v_mul_hi_i32 v178, v161, s51
	s_cselect_b32 s42, s42, 8
	v_readlane_b32 s43, v254, 59
	v_lshrrev_b32_e32 v179, 31, v178
	v_ashrrev_i32_e32 v178, 11, v178
	s_add_i32 s42, s42, s43
	v_readlane_b32 s39, v254, 42
	v_add_u32_e32 v178, v178, v179
	s_mul_i32 s42, s42, 6
	v_mov_b32_e32 v156, s93
	v_mov_b32_e32 v158, s83
	v_mov_b32_e32 v159, s92
	v_mov_b32_e32 v160, s39
	v_mad_i32_i24 v161, v178, s80, v161
	s_ashr_i32 s43, s42, 31
	v_cndmask_b32_e32 v165, v156, v158, vcc
	v_cndmask_b32_e32 v164, v159, v160, vcc
	v_cmp_gt_i32_e32 vcc, s50, v161
	v_lshl_or_b32 v128, s49, 8, v154
	s_lshl_b64 s[42:43], s[42:43], 12
	v_readlane_b32 s44, v253, 29
	v_ashrrev_i32_e32 v179, 31, v178
	v_cndmask_b32_e64 v180, 24, 20, vcc
	v_ashrrev_i32_e32 v182, 31, v161
	v_add_u32_e32 v184, 0xffffff00, v161
	s_add_u32 s42, s44, s42
	v_readlane_b32 s44, v253, 30
	v_ashrrev_i32_e32 v129, 31, v128
	v_lshlrev_b64 v[178:179], v180, v[178:179]
	v_cndmask_b32_e32 v181, v156, v158, vcc
	v_cndmask_b32_e32 v180, v159, v160, vcc
	v_cndmask_b32_e32 v183, 0, v182, vcc
	v_cndmask_b32_e32 v182, v184, v161, vcc
	s_addc_u32 s43, s44, s43
	v_lshlrev_b64 v[150:151], 2, v[128:129]
	v_lshl_add_u64 v[162:163], v[164:165], 0, v[162:163]
	v_lshlrev_b64 v[164:165], 12, v[166:167]
	v_lshl_add_u64 v[178:179], v[180:181], 0, v[178:179]
	v_lshlrev_b64 v[180:181], 12, v[182:183]
	v_lshl_add_u64 v[128:129], s[42:43], 0, v[150:151]
	v_lshl_add_u64 v[162:163], v[162:163], 0, v[164:165]
	v_lshl_add_u64 v[178:179], v[178:179], 0, v[180:181]
	global_load_dwordx4 v[140:143], v[128:129], off nt
	global_load_dwordx4 v[136:139], v[128:129], off offset:64 nt
	global_load_dwordx4 v[132:135], v[128:129], off offset:512 nt
	s_nop 0
	global_load_dwordx4 v[128:131], v[128:129], off offset:576 nt
	v_lshl_add_u64 v[190:191], v[162:163], 0, v[150:151]
	v_lshl_add_u64 v[194:195], v[178:179], 0, v[150:151]
	global_load_dwordx4 v[162:165], v[190:191], off nt
	global_load_dwordx4 v[166:169], v[190:191], off offset:64 nt
	global_load_dwordx4 v[170:173], v[190:191], off offset:512 nt
	global_load_dwordx4 v[174:177], v[190:191], off offset:576 nt
	global_load_dwordx4 v[178:181], v[194:195], off nt
	global_load_dwordx4 v[182:185], v[194:195], off offset:64 nt
	global_load_dwordx4 v[186:189], v[194:195], off offset:512 nt
	global_load_dwordx4 v[210:213], v[194:195], off offset:576 nt
	v_add_u32_e32 v161, 0x80, v157
	v_readlane_b32 s46, v254, 46
	s_mov_b32 s49, s4
	s_mov_b32 s39, s5
	s_mov_b64 s[44:45], s[40:41]
	s_mov_b64 s[42:43], s[0:1]
	v_readlane_b32 s47, v254, 47
	s_waitcnt vmcnt(0)
; #define MEMBAR() asm volatile("" ::: "memory")
;   DI void operator()(const acc_t& acc, const Unit& u, int wr, int wc, int fr, int fq) const {
;     ...
;     for (int q = 0; q < 4; ++q) {
;       const int ai = q >> 1, mh = q & 1;
;       MEMBAR();
;       f32x4 xv[2][2][2];
; #pragma unroll
;       for (int mm = 0; mm < 2; ++mm) { const int t = row0 + ai * HALF + (2 * mh + mm) * 16;
;         const float* xi = from_input ? xrow_in(p, t) : xrow_ws(p, t);
; #pragma unroll
;         for (int bj = 0; bj < 2; ++bj)
; #pragma unroll
;           for (int n = 0; n < 2; ++n) xv[mm][bj][n] = *(const f32x4*)(xi + col0 + bj * HALF + n * 16); }
;       MEMBAR();
; #pragma unroll
;       for (int mm = 0; mm < 2; ++mm) { const int t = row0 + ai * HALF + (2 * mh + mm) * 16;
;         float* xo = xrow_ws(p, t);
; #pragma unroll
;         for (int bj = 0; bj < 2; ++bj)
; #pragma unroll
;           for (int n = 0; n < 2; ++n) *(f32x4*)(xo + col0 + bj * HALF + n * 16) = xv[mm][bj][n] + gv[bj][n] * acc[ai][bj][2 * mh + mm][n]; }
;     }
	v_pk_fma_f32 v[126:127], v[126:127], v[142:143], v[164:165]
	v_pk_fma_f32 v[124:125], v[124:125], v[140:141], v[162:163]
	v_pk_fma_f32 v[122:123], v[122:123], v[138:139], v[168:169]
	v_pk_fma_f32 v[120:121], v[120:121], v[136:137], v[166:167]
	v_pk_fma_f32 v[98:99], v[98:99], v[130:131], v[212:213]
	v_pk_fma_f32 v[96:97], v[96:97], v[128:129], v[210:211]
	v_pk_fma_f32 v[114:115], v[114:115], v[134:135], v[172:173]
	v_pk_fma_f32 v[112:113], v[112:113], v[132:133], v[170:171]
	v_pk_fma_f32 v[106:107], v[106:107], v[130:131], v[176:177]
	v_pk_fma_f32 v[104:105], v[104:105], v[128:129], v[174:175]
	v_pk_fma_f32 v[118:119], v[118:119], v[142:143], v[180:181]
	v_pk_fma_f32 v[116:117], v[116:117], v[140:141], v[178:179]
	v_pk_fma_f32 v[110:111], v[110:111], v[138:139], v[184:185]
	v_pk_fma_f32 v[108:109], v[108:109], v[136:137], v[182:183]
	v_pk_fma_f32 v[102:103], v[102:103], v[134:135], v[188:189]
	v_pk_fma_f32 v[100:101], v[100:101], v[132:133], v[186:187]
	global_store_dwordx4 v[190:191], v[124:127], off
	global_store_dwordx4 v[190:191], v[120:123], off offset:64
	global_store_dwordx4 v[190:191], v[112:115], off offset:512
	global_store_dwordx4 v[190:191], v[104:107], off offset:576
	global_store_dwordx4 v[194:195], v[116:119], off
	global_store_dwordx4 v[194:195], v[108:111], off offset:64
	global_store_dwordx4 v[194:195], v[100:103], off offset:512
	global_store_dwordx4 v[194:195], v[96:99], off offset:576
	v_or_b32_e32 v113, 48, v157
	v_mul_hi_i32 v112, v113, s51
	v_or_b32_e32 v97, 32, v157
	v_mul_hi_i32 v96, v97, s51
	v_lshrrev_b32_e32 v98, 31, v96
	v_ashrrev_i32_e32 v96, 11, v96
	v_add_u32_e32 v96, v96, v98
	v_lshrrev_b32_e32 v114, 31, v112
	v_ashrrev_i32_e32 v112, 11, v112
	v_mad_i32_i24 v100, v96, s80, v97
	v_add_u32_e32 v112, v112, v114
	v_ashrrev_i32_e32 v101, 31, v100
	v_add_u32_e32 v102, 0xffffff00, v100
	v_cmp_gt_i32_e32 vcc, s50, v100
	v_mad_i32_i24 v116, v112, s80, v113
	v_ashrrev_i32_e32 v97, 31, v96
	v_cndmask_b32_e32 v99, v156, v158, vcc
	v_cndmask_b32_e32 v98, v159, v160, vcc
	v_cndmask_b32_e32 v101, 0, v101, vcc
	v_cndmask_b32_e32 v100, v102, v100, vcc
	v_cndmask_b32_e64 v102, 24, 20, vcc
	v_cmp_gt_i32_e32 vcc, s50, v116
	v_ashrrev_i32_e32 v113, 31, v112
	v_ashrrev_i32_e32 v117, 31, v116
	v_cndmask_b32_e64 v114, 24, 20, vcc
	v_add_u32_e32 v118, 0xffffff00, v116
	v_lshlrev_b64 v[96:97], v102, v[96:97]
	v_lshlrev_b64 v[112:113], v114, v[112:113]
	v_cndmask_b32_e32 v115, v156, v158, vcc
	v_cndmask_b32_e32 v114, v159, v160, vcc
	v_cndmask_b32_e32 v117, 0, v117, vcc
	v_cndmask_b32_e32 v116, v118, v116, vcc
	v_lshl_add_u64 v[96:97], v[98:99], 0, v[96:97]
	v_lshlrev_b64 v[98:99], 12, v[100:101]
	v_lshl_add_u64 v[112:113], v[114:115], 0, v[112:113]
	v_lshlrev_b64 v[114:115], 12, v[116:117]
	v_lshl_add_u64 v[96:97], v[96:97], 0, v[98:99]
	v_lshl_add_u64 v[112:113], v[112:113], 0, v[114:115]
	v_lshl_add_u64 v[162:163], v[96:97], 0, v[150:151]
	v_lshl_add_u64 v[164:165], v[112:113], 0, v[150:151]
	global_load_dwordx4 v[96:99], v[162:163], off nt
	global_load_dwordx4 v[100:103], v[162:163], off offset:64 nt
	global_load_dwordx4 v[104:107], v[162:163], off offset:512 nt
	global_load_dwordx4 v[108:111], v[162:163], off offset:576 nt
	global_load_dwordx4 v[112:115], v[164:165], off nt
	global_load_dwordx4 v[116:119], v[164:165], off offset:64 nt
	global_load_dwordx4 v[120:123], v[164:165], off offset:512 nt
	global_load_dwordx4 v[124:127], v[164:165], off offset:576 nt
	v_mul_hi_i32 v166, v161, s51
	v_lshrrev_b32_e32 v167, 31, v166
	v_ashrrev_i32_e32 v166, 11, v166
	v_add_u32_e32 v166, v166, v167
	v_ashrrev_i32_e32 v167, 31, v166
	s_waitcnt vmcnt(0)
	v_pk_fma_f32 v[94:95], v[94:95], v[142:143], v[98:99]
	v_pk_fma_f32 v[92:93], v[92:93], v[140:141], v[96:97]
	v_pk_fma_f32 v[80:81], v[80:81], v[136:137], v[116:117]
	v_pk_fma_f32 v[90:91], v[90:91], v[138:139], v[102:103]
	v_pk_fma_f32 v[88:89], v[88:89], v[136:137], v[100:101]
	v_pk_fma_f32 v[78:79], v[78:79], v[134:135], v[106:107]
	v_pk_fma_f32 v[76:77], v[76:77], v[132:133], v[104:105]
	v_pk_fma_f32 v[74:75], v[74:75], v[130:131], v[110:111]
	v_pk_fma_f32 v[72:73], v[72:73], v[128:129], v[108:109]
	v_pk_fma_f32 v[86:87], v[86:87], v[142:143], v[114:115]
	v_pk_fma_f32 v[84:85], v[84:85], v[140:141], v[112:113]
	v_pk_fma_f32 v[82:83], v[82:83], v[138:139], v[118:119]
	v_pk_fma_f32 v[70:71], v[70:71], v[134:135], v[122:123]
	v_pk_fma_f32 v[68:69], v[68:69], v[132:133], v[120:121]
	v_pk_fma_f32 v[66:67], v[66:67], v[130:131], v[126:127]
	v_pk_fma_f32 v[64:65], v[64:65], v[128:129], v[124:125]
	global_store_dwordx4 v[162:163], v[92:95], off
	global_store_dwordx4 v[162:163], v[88:91], off offset:64
	global_store_dwordx4 v[162:163], v[76:79], off offset:512
	global_store_dwordx4 v[162:163], v[72:75], off offset:576
	global_store_dwordx4 v[164:165], v[84:87], off
	global_store_dwordx4 v[164:165], v[80:83], off offset:64
	global_store_dwordx4 v[164:165], v[68:71], off offset:512
	global_store_dwordx4 v[164:165], v[64:67], off offset:576
	v_add_u32_e32 v81, 0x90, v157
	v_mul_hi_i32 v80, v81, s51
	v_lshrrev_b32_e32 v82, 31, v80
	v_ashrrev_i32_e32 v80, 11, v80
	v_mad_i32_i24 v66, v166, s80, v161
	v_add_u32_e32 v80, v80, v82
	v_ashrrev_i32_e32 v67, 31, v66
	v_add_u32_e32 v68, 0xffffff00, v66
	v_cmp_gt_i32_e32 vcc, s50, v66
	v_mad_i32_i24 v84, v80, s80, v81
	v_ashrrev_i32_e32 v81, 31, v80
	v_cndmask_b32_e32 v65, v156, v158, vcc
	v_cndmask_b32_e32 v64, v159, v160, vcc
	v_cndmask_b32_e32 v67, 0, v67, vcc
	v_cndmask_b32_e32 v66, v68, v66, vcc
	v_cndmask_b32_e64 v68, 24, 20, vcc
	v_cmp_gt_i32_e32 vcc, s50, v84
	v_ashrrev_i32_e32 v85, 31, v84
	v_add_u32_e32 v86, 0xffffff00, v84
	v_cndmask_b32_e64 v82, 24, 20, vcc
; #define MEMBAR() asm volatile("" ::: "memory")
;   DI void operator()(const acc_t& acc, const Unit& u, int wr, int wc, int fr, int fq) const {
;     ...
;     for (int q = 0; q < 4; ++q) {
;       const int ai = q >> 1, mh = q & 1;
;       MEMBAR();
;       f32x4 xv[2][2][2];
; #pragma unroll
;       for (int mm = 0; mm < 2; ++mm) { const int t = row0 + ai * HALF + (2 * mh + mm) * 16;
;         const float* xi = from_input ? xrow_in(p, t) : xrow_ws(p, t);
; #pragma unroll
;         for (int bj = 0; bj < 2; ++bj)
; #pragma unroll
;           for (int n = 0; n < 2; ++n) xv[mm][bj][n] = *(const f32x4*)(xi + col0 + bj * HALF + n * 16); }
;       MEMBAR();
; #pragma unroll
;       for (int mm = 0; mm < 2; ++mm) { const int t = row0 + ai * HALF + (2 * mh + mm) * 16;
;         float* xo = xrow_ws(p, t);
; #pragma unroll
;         for (int bj = 0; bj < 2; ++bj)
; #pragma unroll
;           for (int n = 0; n < 2; ++n) *(f32x4*)(xo + col0 + bj * HALF + n * 16) = xv[mm][bj][n] + gv[bj][n] * acc[ai][bj][2 * mh + mm][n]; }
;     }
	v_lshlrev_b64 v[68:69], v68, v[166:167]
	v_lshlrev_b64 v[80:81], v82, v[80:81]
	v_cndmask_b32_e32 v83, v156, v158, vcc
	v_cndmask_b32_e32 v82, v159, v160, vcc
	v_cndmask_b32_e32 v85, 0, v85, vcc
	v_cndmask_b32_e32 v84, v86, v84, vcc
	v_lshl_add_u64 v[64:65], v[64:65], 0, v[68:69]
	v_lshlrev_b64 v[66:67], 12, v[66:67]
	v_lshl_add_u64 v[80:81], v[82:83], 0, v[80:81]
	v_lshlrev_b64 v[82:83], 12, v[84:85]
	v_lshl_add_u64 v[64:65], v[64:65], 0, v[66:67]
	v_lshl_add_u64 v[80:81], v[80:81], 0, v[82:83]
	v_lshl_add_u64 v[96:97], v[64:65], 0, v[150:151]
	v_lshl_add_u64 v[98:99], v[80:81], 0, v[150:151]
	global_load_dwordx4 v[64:67], v[96:97], off nt
	global_load_dwordx4 v[68:71], v[96:97], off offset:64 nt
	global_load_dwordx4 v[72:75], v[96:97], off offset:512 nt
	global_load_dwordx4 v[76:79], v[96:97], off offset:576 nt
	global_load_dwordx4 v[80:83], v[98:99], off nt
	global_load_dwordx4 v[84:87], v[98:99], off offset:64 nt
	global_load_dwordx4 v[88:91], v[98:99], off offset:512 nt
	global_load_dwordx4 v[92:95], v[98:99], off offset:576 nt
	v_add_u32_e32 v101, 0xa0, v157
	v_mul_hi_i32 v100, v101, s51
	v_lshrrev_b32_e32 v102, 31, v100
	v_ashrrev_i32_e32 v100, 11, v100
	v_add_u32_e32 v100, v100, v102
	v_mad_i32_i24 v104, v100, s80, v101
	v_ashrrev_i32_e32 v105, 31, v104
	v_add_u32_e32 v106, 0xffffff00, v104
	v_cmp_gt_i32_e32 vcc, s50, v104
	v_ashrrev_i32_e32 v101, 31, v100
	s_waitcnt vmcnt(0)
	v_pk_fma_f32 v[62:63], v[62:63], v[142:143], v[66:67]
	v_pk_fma_f32 v[60:61], v[60:61], v[140:141], v[64:65]
	v_pk_fma_f32 v[48:49], v[48:49], v[136:137], v[84:85]
	v_pk_fma_f32 v[58:59], v[58:59], v[138:139], v[70:71]
	v_pk_fma_f32 v[56:57], v[56:57], v[136:137], v[68:69]
	v_pk_fma_f32 v[46:47], v[46:47], v[134:135], v[74:75]
	v_pk_fma_f32 v[44:45], v[44:45], v[132:133], v[72:73]
	v_pk_fma_f32 v[42:43], v[42:43], v[130:131], v[78:79]
	v_pk_fma_f32 v[40:41], v[40:41], v[128:129], v[76:77]
	v_pk_fma_f32 v[54:55], v[54:55], v[142:143], v[82:83]
	v_pk_fma_f32 v[52:53], v[52:53], v[140:141], v[80:81]
	v_pk_fma_f32 v[50:51], v[50:51], v[138:139], v[86:87]
	v_pk_fma_f32 v[38:39], v[38:39], v[134:135], v[90:91]
	v_pk_fma_f32 v[36:37], v[36:37], v[132:133], v[88:89]
	v_pk_fma_f32 v[34:35], v[34:35], v[130:131], v[94:95]
	v_pk_fma_f32 v[32:33], v[32:33], v[128:129], v[92:93]
	global_store_dwordx4 v[96:97], v[60:63], off
	global_store_dwordx4 v[96:97], v[56:59], off offset:64
	global_store_dwordx4 v[96:97], v[44:47], off offset:512
	global_store_dwordx4 v[96:97], v[40:43], off offset:576
	global_store_dwordx4 v[98:99], v[52:55], off
	global_store_dwordx4 v[98:99], v[48:51], off offset:64
	global_store_dwordx4 v[98:99], v[36:39], off offset:512
	global_store_dwordx4 v[98:99], v[32:35], off offset:576
	v_add_u32_e32 v49, 0xb0, v157
	v_mul_hi_i32 v48, v49, s51
	v_lshrrev_b32_e32 v50, 31, v48
	v_ashrrev_i32_e32 v48, 11, v48
	v_add_u32_e32 v48, v48, v50
	v_mad_i32_i24 v52, v48, s80, v49
	v_cndmask_b32_e32 v103, v156, v158, vcc
	v_cndmask_b32_e32 v102, v159, v160, vcc
	v_cndmask_b32_e32 v105, 0, v105, vcc
	v_cndmask_b32_e32 v104, v106, v104, vcc
	v_cndmask_b32_e64 v32, 24, 20, vcc
	v_cmp_gt_i32_e32 vcc, s50, v52
	v_ashrrev_i32_e32 v49, 31, v48
	v_ashrrev_i32_e32 v53, 31, v52
	v_cndmask_b32_e64 v50, 24, 20, vcc
	v_add_u32_e32 v54, 0xffffff00, v52
	v_lshlrev_b64 v[32:33], v32, v[100:101]
	v_lshlrev_b64 v[48:49], v50, v[48:49]
	v_cndmask_b32_e32 v51, v156, v158, vcc
	v_cndmask_b32_e32 v50, v159, v160, vcc
	v_cndmask_b32_e32 v53, 0, v53, vcc
	v_cndmask_b32_e32 v52, v54, v52, vcc
	v_lshl_add_u64 v[32:33], v[102:103], 0, v[32:33]
	v_lshlrev_b64 v[34:35], 12, v[104:105]
	v_lshl_add_u64 v[48:49], v[50:51], 0, v[48:49]
	v_lshlrev_b64 v[50:51], 12, v[52:53]
	v_lshl_add_u64 v[32:33], v[32:33], 0, v[34:35]
	v_lshl_add_u64 v[48:49], v[48:49], 0, v[50:51]
	v_lshl_add_u64 v[64:65], v[32:33], 0, v[150:151]
	v_lshl_add_u64 v[66:67], v[48:49], 0, v[150:151]
	global_load_dwordx4 v[32:35], v[64:65], off nt
	global_load_dwordx4 v[36:39], v[64:65], off offset:64 nt
	global_load_dwordx4 v[40:43], v[64:65], off offset:512 nt
	global_load_dwordx4 v[44:47], v[64:65], off offset:576 nt
	global_load_dwordx4 v[48:51], v[66:67], off nt
	global_load_dwordx4 v[52:55], v[66:67], off offset:64 nt
	global_load_dwordx4 v[56:59], v[66:67], off offset:512 nt
	global_load_dwordx4 v[60:63], v[66:67], off offset:576 nt
	s_and_b64 vcc, exec, s[36:37]
	s_waitcnt vmcnt(0)
	v_pk_fma_f32 v[30:31], v[30:31], v[142:143], v[34:35]
	v_pk_fma_f32 v[28:29], v[28:29], v[140:141], v[32:33]
	v_pk_fma_f32 v[26:27], v[26:27], v[138:139], v[38:39]
	v_pk_fma_f32 v[24:25], v[24:25], v[136:137], v[36:37]
	v_pk_fma_f32 v[14:15], v[14:15], v[134:135], v[42:43]
	v_pk_fma_f32 v[12:13], v[12:13], v[132:133], v[40:41]
	v_pk_fma_f32 v[10:11], v[10:11], v[130:131], v[46:47]
	v_pk_fma_f32 v[8:9], v[8:9], v[128:129], v[44:45]
	v_pk_fma_f32 v[22:23], v[22:23], v[142:143], v[50:51]
	v_pk_fma_f32 v[20:21], v[20:21], v[140:141], v[48:49]
	v_pk_fma_f32 v[18:19], v[18:19], v[138:139], v[54:55]
	v_pk_fma_f32 v[16:17], v[16:17], v[136:137], v[52:53]
	v_pk_fma_f32 v[6:7], v[6:7], v[134:135], v[58:59]
	v_pk_fma_f32 v[4:5], v[4:5], v[132:133], v[56:57]
	v_pk_fma_f32 v[2:3], v[2:3], v[130:131], v[62:63]
	v_pk_fma_f32 v[0:1], v[0:1], v[128:129], v[60:61]
	global_store_dwordx4 v[64:65], v[28:31], off
	global_store_dwordx4 v[64:65], v[24:27], off offset:64
	global_store_dwordx4 v[64:65], v[12:15], off offset:512
	global_store_dwordx4 v[64:65], v[8:11], off offset:576
	global_store_dwordx4 v[66:67], v[20:23], off
	global_store_dwordx4 v[66:67], v[16:19], off offset:64
	global_store_dwordx4 v[66:67], v[4:7], off offset:512
	global_store_dwordx4 v[66:67], v[0:3], off offset:576
	s_cbranch_vccz .LBB0_1921
	s_waitcnt vmcnt(0)
	s_cmpk_gt_u32 s3, 0xff
	s_cbranch_scc1 .LBB0_1933
	s_barrier

; DI void phase_final_norm(const Params& p) {
;     ...
;   for (int t = blockIdx.x * 8 + w; t < NB * SEQ; t += gridDim.x * 8) {
;     float* xr = p.out + (size_t)t * D;
;     float4 v[4]; float ss = 0.f;
; #pragma unroll
;     for (int i = 0; i < 4; ++i) { v[i] = *(const float4*)(xr + (i * 64 + lane) * 4); ss += v[i].x * v[i].x + v[i].y * v[i].y + v[i].z * v[i].z + v[i].w * v[i].w; }
;     ss = wave_sum(ss);
;     const float rstd = rsqrtf(ss * (1.f / 1024.f) + EPS);
; #pragma unroll
;     for (int i = 0; i < 4; ++i) {
;       const int k = (i * 64 + lane) * 4;
;       float4 o; o.x = v[i].x * rstd * gg[i].x; o.y = v[i].y * rstd * gg[i].y; o.z = v[i].z * rstd * gg[i].z; o.w = v[i].w * rstd * gg[i].w;
;       *(float4*)(xr + k) = o;
;     }
;   }
.LBB0_1987:
	v_ashrrev_i32_e32 v17, 31, v16
	v_lshlrev_b64 v[28:29], 12, v[16:17]
	v_lshl_add_u64 v[44:45], v[18:19], 0, v[28:29]
	global_load_dwordx4 v[28:31], v[44:45], off nt
	global_load_dwordx4 v[32:35], v[44:45], off offset:1024 nt
	global_load_dwordx4 v[36:39], v[44:45], off offset:2048 nt
	global_load_dwordx4 v[40:43], v[44:45], off offset:3072 nt
	v_add_u32_e32 v16, s4, v16
	v_cmp_lt_i32_e64 s[0:1], s6, v16
	s_or_b64 s[2:3], s[0:1], s[2:3]
	s_waitcnt vmcnt(3)
	v_mov_b32_e32 v48, v29
	s_waitcnt vmcnt(2)
	v_mov_b32_e32 v49, v33
	v_mov_b32_e32 v46, v28
	v_mov_b32_e32 v47, v32
	s_waitcnt vmcnt(1)
	v_mov_b32_e32 v56, v37
	s_waitcnt vmcnt(0)
	v_mov_b32_e32 v57, v41
	v_pk_mul_f32 v[48:49], v[48:49], v[48:49]
	v_mov_b32_e32 v50, v30
	v_mov_b32_e32 v51, v34
	v_mov_b32_e32 v54, v36
	v_mov_b32_e32 v55, v40
	v_pk_mul_f32 v[56:57], v[56:57], v[56:57]
	v_pk_fma_f32 v[46:47], v[46:47], v[46:47], v[48:49]
	v_mov_b32_e32 v52, v31
	v_mov_b32_e32 v53, v35
	v_mov_b32_e32 v58, v38
	v_mov_b32_e32 v59, v42
	v_pk_fma_f32 v[48:49], v[54:55], v[54:55], v[56:57]
	v_pk_fma_f32 v[46:47], v[50:51], v[50:51], v[46:47]
	v_mov_b32_e32 v60, v39
	v_mov_b32_e32 v61, v43
	v_pk_fma_f32 v[48:49], v[58:59], v[58:59], v[48:49]
	v_pk_fma_f32 v[46:47], v[52:53], v[52:53], v[46:47]
	v_pk_fma_f32 v[48:49], v[60:61], v[60:61], v[48:49]
	v_add_f32_e32 v17, v46, v47
	v_add_f32_e32 v17, v17, v48
	v_add_f32_e32 v17, v17, v49
	ds_bpermute_b32 v27, v20, v17
	s_waitcnt lgkmcnt(0)
	v_add_f32_e32 v17, v17, v27
	ds_bpermute_b32 v27, v21, v17
	s_waitcnt lgkmcnt(0)
	v_add_f32_e32 v17, v17, v27
	ds_bpermute_b32 v27, v22, v17
	s_waitcnt lgkmcnt(0)
	v_add_f32_e32 v17, v17, v27
	ds_bpermute_b32 v27, v23, v17
	s_waitcnt lgkmcnt(0)
	v_add_f32_e32 v17, v17, v27
	ds_bpermute_b32 v27, v24, v17
	s_waitcnt lgkmcnt(0)
	v_add_f32_e32 v17, v17, v27
	ds_bpermute_b32 v27, v25, v17
	s_waitcnt lgkmcnt(0)
	v_add_f32_e32 v17, v17, v27
	v_fmamk_f32 v17, v17, 0x3a800000, v26
	v_mul_f32_e32 v27, 0x4b800000, v17
	v_cmp_gt_f32_e32 vcc, s5, v17
	s_nop 1
	v_cndmask_b32_e32 v17, v17, v27, vcc
	v_rsq_f32_e32 v17, v17
	s_nop 0
	v_mul_f32_e32 v27, 0x45800000, v17
	v_cndmask_b32_e32 v46, v17, v27, vcc
	v_pk_mul_f32 v[28:29], v[28:29], v[46:47] op_sel_hi:[1,0]
	v_pk_mul_f32 v[30:31], v[30:31], v[46:47] op_sel_hi:[1,0]
	v_pk_mul_f32 v[32:33], v[32:33], v[46:47] op_sel_hi:[1,0]
	v_pk_mul_f32 v[34:35], v[34:35], v[46:47] op_sel_hi:[1,0]
	v_pk_mul_f32 v[36:37], v[36:37], v[46:47] op_sel_hi:[1,0]
	v_pk_mul_f32 v[38:39], v[38:39], v[46:47] op_sel_hi:[1,0]
	v_pk_mul_f32 v[40:41], v[40:41], v[46:47] op_sel_hi:[1,0]
	v_pk_mul_f32 v[42:43], v[42:43], v[46:47] op_sel_hi:[1,0]
	v_pk_mul_f32 v[28:29], v[0:1], v[28:29]
	v_pk_mul_f32 v[30:31], v[2:3], v[30:31]
	v_pk_mul_f32 v[32:33], v[4:5], v[32:33]
	v_pk_mul_f32 v[34:35], v[6:7], v[34:35]
	v_pk_mul_f32 v[36:37], v[8:9], v[36:37]
	v_pk_mul_f32 v[38:39], v[10:11], v[38:39]
	v_pk_mul_f32 v[40:41], v[12:13], v[40:41]
	v_pk_mul_f32 v[42:43], v[14:15], v[42:43]
	global_store_dwordx4 v[44:45], v[28:31], off nt
	global_store_dwordx4 v[44:45], v[32:35], off offset:1024 nt
	global_store_dwordx4 v[44:45], v[36:39], off offset:2048 nt
	global_store_dwordx4 v[44:45], v[40:43], off offset:3072 nt
	s_andn2_b64 exec, exec, s[2:3]
	s_cbranch_execnz .LBB0_1987
